# x20: as x17 plus V LDS image in natural key order so P fragments need no permlane swaps; leaner scalar address math
# speedup vs baseline: 1.0414x; 1.0008x over previous
; __device__ __forceinline__ int fresh_tid() { int t = threadIdx.x; asm volatile("" : "+v"(t)); return t; }
; __device__ __forceinline__ int v_st(int k, int c) { const int kk = (k & ~0xC) | ((k & 4) << 1) | ((k & 8) >> 1); return ((kk >> 3) * 4 + (c >> 5)) * 512 + ((kk & 7) * 32 + (c & 31)) * 2; }
; __device__ __forceinline__ int v_rd_base(int lane) { return ((lane & 3) << 3) | (((lane >> 2) & 3) << 6) | (((lane >> 4) & 1) << 5) | (((lane >> 5) & 1) << 8); }
; #define SLOAD(i, j) do { const long kr_ = KROW(j); sr_[i].vs0 = ld8(Vp + (kr_ + sr) * ldv + sc); sr_[i].ks0 = ld8(Kp + (kr_ + sr) * ldk + sc); \
;     if (DQK == 96) sr_[i].ks1 = ld8(Kp + (kr_ + sr2) * ldk + sc2); } while (0)
; #define SWRITE(b, i) do { *(bf16x8*)(V_lds + (b) * SHM_V + vst0) = sr_[i].vs0; *(bf16x8*)(K_lds + (b) * SHM_K + kst0) = sr_[i].ks0; \
;     if (DQK == 96) *(bf16x8*)(K_lds + (b) * SHM_K + kst1) = sr_[i].ks1; } while (0)
; template <int DQK, int MODE, int ldq, int ldk, int ldv> ...
;     ...
;   const int tid = fresh_tid(), wid = tid >> 6, lane = tid & 63, r32 = lane & 31, hi = lane >> 5;
;   char* V_lds = lds; char* K_lds = lds + 2 * SHM_V;
;   float* ws = (float*)(lds + 2 * SHM_V + 2 * SHM_K) + wid * 64; float* li_l = ws; float* al_l = ws + 32;
;   float m_reg = -1e30f, l_reg = 0; f32x16 o[2] = {}; bf16x8 qr[DQK / 16];
;   const bf16_t* Qw = Qb + (long)(wid * QBLK + r32) * ldq + hi * 8;
; #pragma unroll
;   for (int d0 = 0; d0 < DQK / 16; ++d0) qr[d0] = ld8(Qw + d0 * 16);
;   NaInfo na; na.brow = (const float*)(lds + rpb_off); na.qr = r0 + (wid >> 1); na.qc = (wid & 1) * 32 + r32;
;   const int sr = tid >> 3, sc = (tid & 7) * 8, vst0 = v_st(sr, sc), kst0 = KSWZ(sr, sc * 2);
;   const int sr2 = (tid & 255) >> 2, sc2 = 64 + (tid & 3) * 8, kst1 = KSWZ(sr2, sc2 * 2);
;   const int vb0 = (int)(uintptr_t)V_lds + v_rd_base(lane);
;   struct { bf16x8 vs0, ks0, ks1; } sr_[2];
;     ...
;   f32x16 pA0, pA1, pB0, pB1; float mnA, mnB, alA, alB; bf16x8 pa0, pa1, pa2, pa3;
;   constexpr int SE = 0, SO = 1;
;   SLOAD(SE, 0); SLOAD(SO, 1); asm volatile("s_waitcnt vmcnt(0)" ::: "memory"); SWRITE(0, SE); SWRITE(1, SO);
.LBB0_299:
	v_readfirstlane_b32 s32, v234
	s_nop 0
	s_lshr_b32 s32, s32, 8
	s_ashr_i32 s11, s22, 7
	s_lshl_b32 s0, s22, 8
	s_lshl_b32 s10, s11, 13
	s_and_b32 s0, s0, 0x1f00
	s_or_b32 s6, s10, s0
	s_bfe_u32 s4, s22, 0x20005
	s_ashr_i32 s7, s6, 31
	s_mul_i32 s1, s6, 0x300
	s_mul_hi_i32 s0, s6, 0x300
	s_add_u32 s1, s16, s1
	s_addc_u32 s0, s17, s0
	s_mul_i32 s5, s4, 0xc0
	s_add_u32 s12, s1, s5
	s_addc_u32 s13, s0, 0
	s_add_u32 s0, s18, s5
	s_addc_u32 s1, s19, 0
	s_lshl_b32 s23, s4, 6
	s_lshl_b32 s4, s4, 7
	s_add_u32 s4, s20, s4
	s_addc_u32 s5, s21, 0
	s_lshl_b32 s24, s11, 8
	s_add_i32 s24, s24, 0x6000
	v_mov_b32_e32 v52, v234
	s_add_i32 s26, 0, 0x10000
	s_cmp_lg_u32 0, -1
	v_ashrrev_i32_e32 v130, 3, v52
	v_lshlrev_b32_e32 v28, 3, v52
	v_and_b32_e32 v0, 56, v28
	v_bfe_u32 v132, v52, 2, 6
	s_cselect_b32 s25, 0, 0
	s_ashr_i32 s11, s10, 31
	v_ashrrev_i32_e32 v131, 31, v130
	s_waitcnt lgkmcnt(0)
	v_lshlrev_b32_e32 v48, 1, v0
	v_lshl_add_u64 v[0:1], v[130:131], 0, s[10:11]
	v_mov_b64_e32 v[24:25], s[0:1]
	v_or_b32_e32 v8, s10, v132
	v_mad_u64_u32 v[4:5], s[28:29], v0, s70, v[24:25]
	v_mad_i64_i32 v[8:9], s[28:29], v8, s70, v[24:25]
	s_or_b32 s28, s10, 64
	s_ashr_i32 s29, s28, 31
	v_lshl_add_u64 v[16:17], v[130:131], 0, s[28:29]
	v_lshlrev_b64 v[2:3], 9, v[0:1]
	v_mad_u64_u32 v[18:19], s[30:31], v16, s70, v[24:25]
	v_lshl_add_u64 v[2:3], s[4:5], 0, v[2:3]
	v_mov_b32_e32 v49, v205
	v_mad_i32_i24 v5, v1, s70, v5
	v_mad_i32_i24 v19, v17, s70, v19
	v_lshlrev_b32_e32 v53, 4, v52
	v_lshl_add_u64 v[2:3], v[2:3], 0, v[48:49]
	v_lshl_add_u64 v[4:5], v[4:5], 0, v[48:49]
	v_lshlrev_b64 v[10:11], 9, v[16:17]
	v_lshl_add_u64 v[16:17], v[18:19], 0, v[48:49]
	v_or_b32_e32 v18, s28, v132
	v_and_b32_e32 v50, 48, v53
	global_load_dwordx4 v[0:3], v[2:3], off
	s_nop 0
	global_load_dwordx4 v[4:7], v[4:5], off
	v_mov_b32_e32 v51, v205
	v_lshl_add_u64 v[10:11], s[4:5], 0, v[10:11]
	v_mad_i64_i32 v[18:19], s[28:29], v18, s70, v[24:25]
	v_lshl_add_u64 v[8:9], v[8:9], 0, v[50:51]
	v_lshl_add_u64 v[12:13], v[10:11], 0, v[48:49]
	v_lshl_add_u64 v[20:21], v[18:19], 0, v[50:51]
	global_load_dwordx4 v[8:11], v[8:9], off offset:128
	s_nop 0
	global_load_dwordx4 v[12:15], v[12:13], off
	s_nop 0
	global_load_dwordx4 v[16:19], v[16:17], off
	s_nop 0
	global_load_dwordx4 v[20:23], v[20:21], off offset:128
	v_ashrrev_i32_e32 v54, 1, v52
	s_movk_i32 s11, 0xffe0
	v_bfe_u32 v133, v52, 5, 1
	v_bfi_b32 v29, s11, v54, v52
	v_mov_b64_e32 v[26:27], s[12:13]
	v_mad_i64_i32 v[26:27], s[12:13], v29, s70, v[26:27]
	v_lshlrev_b32_e32 v204, 4, v133
	v_lshl_add_u64 v[26:27], v[26:27], 0, v[204:205]
	global_load_dwordx4 v[84:87], v[26:27], off
	global_load_dwordx4 v[80:83], v[26:27], off offset:32
	global_load_dwordx4 v[76:79], v[26:27], off offset:64
	global_load_dwordx4 v[72:75], v[26:27], off offset:96
	global_load_dwordx4 v[68:71], v[26:27], off offset:128
	global_load_dwordx4 v[64:67], v[26:27], off offset:160
	v_and_b32_e32 v26, 0xfffff0, v130
	v_lshlrev_b32_e32 v27, 1, v130
	v_and_or_b32 v26, v27, 8, v26
	v_lshrrev_b32_e32 v26, 1, v26
	v_bfe_u32 v28, v28, 5, 1
	v_lshrrev_b32_e32 v27, 1, v130
	v_or_b32_e32 v26, v26, v28
	v_and_b32_e32 v28, 3, v130
	v_and_or_b32 v27, v27, 4, v28
	v_and_b32_e32 v28, 48, v48
	v_lshl_or_b32 v27, v27, 6, v28
	v_lshlrev_b32_e32 v28, 4, v130
	v_lshl_or_b32 v26, v26, 9, v27
	v_lshlrev_b32_e32 v27, 8, v130
	v_and_b32_e32 v28, 0xf0, v28
	s_or_b32 s12, s10, 0x80
	v_bitop3_b32 v27, v48, v27, v28 bitop3:0xde
	v_lshlrev_b32_e32 v30, 2, v52
	v_add_u32_e32 v145, 0, v26
	v_lshrrev_b32_e32 v145, 6, v234
	v_lshlrev_b32_e32 v145, 11, v145
	v_bfe_u32 v184, v234, 2, 1
	v_lshl_or_b32 v145, v184, 9, v145
	v_bfe_u32 v184, v234, 3, 3
	v_lshl_or_b32 v145, v184, 6, v145
	v_and_b32_e32 v184, 3, v234
	v_lshl_or_b32 v145, v184, 4, v145
	s_ashr_i32 s13, s12, 31
	v_lshlrev_b32_e32 v28, 8, v132
	v_or_b32_e32 v29, 0x80, v50
	v_and_b32_e32 v30, 0xf0, v30
	s_waitcnt vmcnt(0)
	v_add_u32_e32 v146, 0, v27
	v_bitop3_b32 v28, v29, v28, v30 bitop3:0xde
	v_add_u32_e32 v147, 0, v28
	v_and_b32_e32 v140, 31, v52
	v_and_b32_e32 v56, 63, v52
	v_and_b32_e32 v128, 0xffffffe0, v54
	v_readlane_b32 s76, v255, 19
	v_readlane_b32 s77, v255, 20
	v_readlane_b32 s78, v255, 21
	v_readlane_b32 s79, v255, 22
	v_readlane_b32 s80, v255, 23
	v_readlane_b32 s81, v255, 24
	v_readlane_b32 s82, v255, 25
	v_readlane_b32 s83, v255, 26
	v_readlane_b32 s84, v255, 27
	v_readlane_b32 s85, v255, 28
	v_readlane_b32 s86, v255, 29
	v_readlane_b32 s87, v255, 30
	v_readlane_b32 s88, v255, 31
	v_readlane_b32 s89, v255, 32
	v_readlane_b32 s90, v255, 33
	v_readlane_b32 s91, v255, 34
	s_mov_b32 s76, s77
	s_mov_b32 s78, s77
	s_mov_b32 s79, s77
	s_mov_b32 s80, s77
	s_mov_b32 s81, s77
	s_mov_b32 s82, s77
	s_mov_b32 s83, s77
	s_mov_b32 s84, s77
	s_mov_b32 s85, s77
	s_mov_b32 s86, s77
	s_mov_b32 s87, s77
	s_mov_b32 s88, s77
	s_waitcnt vmcnt(0)
; #define SLOAD(i, j) do { const long kr_ = KROW(j); sr_[i].vs0 = ld8(Vp + (kr_ + sr) * ldv + sc); sr_[i].ks0 = ld8(Kp + (kr_ + sr) * ldk + sc); \
;     if (DQK == 96) sr_[i].ks1 = ld8(Kp + (kr_ + sr2) * ldk + sc2); } while (0)
; #define SWRITE(b, i) do { *(bf16x8*)(V_lds + (b) * SHM_V + vst0) = sr_[i].vs0; *(bf16x8*)(K_lds + (b) * SHM_K + kst0) = sr_[i].ks0; \
;     if (DQK == 96) *(bf16x8*)(K_lds + (b) * SHM_K + kst1) = sr_[i].ks1; } while (0)
; template <int DQK, int MODE, int ldq, int ldk, int ldv> ...
;     ...
;   const bf16_t* Qw = Qb + (long)(wid * QBLK + r32) * ldq + hi * 8;
; #pragma unroll
;   for (int d0 = 0; d0 < DQK / 16; ++d0) qr[d0] = ld8(Qw + d0 * 16);
;     ...
;   f32x16 pA0, pA1, pB0, pB1; float mnA, mnB, alA, alB; bf16x8 pa0, pa1, pa2, pa3;
;   constexpr int SE = 0, SO = 1;
;   SLOAD(SE, 0); SLOAD(SO, 1); asm volatile("s_waitcnt vmcnt(0)" ::: "memory"); SWRITE(0, SE); SWRITE(1, SO);
;   if (2 < NT) SLOAD(SE, 2);
	ds_write_b128 v145, v[0:3]
	v_lshl_add_u64 v[0:1], v[130:131], 0, s[12:13]
	ds_write_b128 v146, v[4:7] offset:32768
	v_lshlrev_b64 v[2:3], 9, v[0:1]
	v_mad_u64_u32 v[4:5], s[28:29], v0, s70, v[24:25]
	v_lshl_add_u64 v[2:3], s[4:5], 0, v[2:3]
	v_mad_i32_i24 v5, v1, s70, v5
	ds_write_b128 v147, v[8:11] offset:32768
	ds_write_b128 v145, v[12:15] offset:16384
	ds_write_b128 v146, v[16:19] offset:49152
	ds_write_b128 v147, v[20:23] offset:49152
	v_lshl_add_u64 v[2:3], v[2:3], 0, v[48:49]
	s_mov_b32 s98, 0xffff8000
	s_mov_b32 s99, -1
	v_lshl_add_u64 v[2:3], v[2:3], 0, s[98:99]
	v_lshl_add_u64 v[0:1], v[4:5], 0, v[48:49]
	global_load_dwordx4 v[92:95], v[2:3], off
	global_load_dwordx4 v[88:91], v[0:1], off
	v_or_b32_e32 v0, s12, v132
	v_mad_i64_i32 v[0:1], s[12:13], v0, s70, v[24:25]
	v_lshl_add_u64 v[0:1], v[0:1], 0, v[50:51]
	v_lshlrev_b32_e32 v8, 8, v140
	v_and_b32_e32 v9, 0xf0, v53
	global_load_dwordx4 v[96:99], v[0:1], off offset:128
	v_bitop3_b32 v0, v204, v8, v9 bitop3:0xde
	v_add_u32_e32 v148, 0, v0
	v_lshlrev_b32_e32 v12, 16, v64
	v_and_b32_e32 v13, 0xffff0000, v64
	v_mul_f32_e32 v12, 0x3e16c740, v12
	v_mul_f32_e32 v13, 0x3e16c740, v13
	v_cvt_pk_bf16_f32 v64, v12, v13
	v_lshlrev_b32_e32 v12, 16, v65
	v_and_b32_e32 v13, 0xffff0000, v65
	v_mul_f32_e32 v12, 0x3e16c740, v12
	v_mul_f32_e32 v13, 0x3e16c740, v13
	v_cvt_pk_bf16_f32 v65, v12, v13
	v_lshlrev_b32_e32 v12, 16, v66
	v_and_b32_e32 v13, 0xffff0000, v66
	v_mul_f32_e32 v12, 0x3e16c740, v12
	v_mul_f32_e32 v13, 0x3e16c740, v13
	v_cvt_pk_bf16_f32 v66, v12, v13
	v_lshlrev_b32_e32 v12, 16, v67
	v_and_b32_e32 v13, 0xffff0000, v67
	v_mul_f32_e32 v12, 0x3e16c740, v12
	v_mul_f32_e32 v13, 0x3e16c740, v13
	v_cvt_pk_bf16_f32 v67, v12, v13
	v_lshlrev_b32_e32 v12, 16, v68
	v_and_b32_e32 v13, 0xffff0000, v68
	v_mul_f32_e32 v12, 0x3e16c740, v12
	v_mul_f32_e32 v13, 0x3e16c740, v13
	v_cvt_pk_bf16_f32 v68, v12, v13
	v_lshlrev_b32_e32 v12, 16, v69
	v_and_b32_e32 v13, 0xffff0000, v69
	v_mul_f32_e32 v12, 0x3e16c740, v12
	v_mul_f32_e32 v13, 0x3e16c740, v13
	v_cvt_pk_bf16_f32 v69, v12, v13
	v_lshlrev_b32_e32 v12, 16, v70
	v_and_b32_e32 v13, 0xffff0000, v70
	v_mul_f32_e32 v12, 0x3e16c740, v12
	v_mul_f32_e32 v13, 0x3e16c740, v13
	v_cvt_pk_bf16_f32 v70, v12, v13
	v_lshlrev_b32_e32 v12, 16, v71
	v_and_b32_e32 v13, 0xffff0000, v71
	v_mul_f32_e32 v12, 0x3e16c740, v12
	v_mul_f32_e32 v13, 0x3e16c740, v13
	v_cvt_pk_bf16_f32 v71, v12, v13
	v_lshlrev_b32_e32 v12, 16, v72
	v_and_b32_e32 v13, 0xffff0000, v72
	v_mul_f32_e32 v12, 0x3e16c740, v12
	v_mul_f32_e32 v13, 0x3e16c740, v13
	v_cvt_pk_bf16_f32 v72, v12, v13
	v_lshlrev_b32_e32 v12, 16, v73
	v_and_b32_e32 v13, 0xffff0000, v73
	v_mul_f32_e32 v12, 0x3e16c740, v12
	v_mul_f32_e32 v13, 0x3e16c740, v13
	v_cvt_pk_bf16_f32 v73, v12, v13
	v_lshlrev_b32_e32 v12, 16, v74
	v_and_b32_e32 v13, 0xffff0000, v74
	v_mul_f32_e32 v12, 0x3e16c740, v12
	v_mul_f32_e32 v13, 0x3e16c740, v13
	v_cvt_pk_bf16_f32 v74, v12, v13
	v_lshlrev_b32_e32 v12, 16, v75
	v_and_b32_e32 v13, 0xffff0000, v75
	v_mul_f32_e32 v12, 0x3e16c740, v12
	v_mul_f32_e32 v13, 0x3e16c740, v13
	v_cvt_pk_bf16_f32 v75, v12, v13
	v_lshlrev_b32_e32 v12, 16, v76
	v_and_b32_e32 v13, 0xffff0000, v76
	v_mul_f32_e32 v12, 0x3e16c740, v12
	v_mul_f32_e32 v13, 0x3e16c740, v13
	v_cvt_pk_bf16_f32 v76, v12, v13
	v_lshlrev_b32_e32 v12, 16, v77
	v_and_b32_e32 v13, 0xffff0000, v77
	v_mul_f32_e32 v12, 0x3e16c740, v12
	v_mul_f32_e32 v13, 0x3e16c740, v13
	v_cvt_pk_bf16_f32 v77, v12, v13
	v_lshlrev_b32_e32 v12, 16, v78
	v_and_b32_e32 v13, 0xffff0000, v78
	v_mul_f32_e32 v12, 0x3e16c740, v12
	v_mul_f32_e32 v13, 0x3e16c740, v13
	v_cvt_pk_bf16_f32 v78, v12, v13
	v_lshlrev_b32_e32 v12, 16, v79
	v_and_b32_e32 v13, 0xffff0000, v79
	v_mul_f32_e32 v12, 0x3e16c740, v12
	v_mul_f32_e32 v13, 0x3e16c740, v13
	v_cvt_pk_bf16_f32 v79, v12, v13
	v_lshlrev_b32_e32 v12, 16, v80
	v_and_b32_e32 v13, 0xffff0000, v80
	v_mul_f32_e32 v12, 0x3e16c740, v12
	v_mul_f32_e32 v13, 0x3e16c740, v13
	v_cvt_pk_bf16_f32 v80, v12, v13
	v_lshlrev_b32_e32 v12, 16, v81
	v_and_b32_e32 v13, 0xffff0000, v81
	v_mul_f32_e32 v12, 0x3e16c740, v12
	v_mul_f32_e32 v13, 0x3e16c740, v13
	v_cvt_pk_bf16_f32 v81, v12, v13
	v_lshlrev_b32_e32 v12, 16, v82
	v_and_b32_e32 v13, 0xffff0000, v82
	v_mul_f32_e32 v12, 0x3e16c740, v12
	v_mul_f32_e32 v13, 0x3e16c740, v13
	v_cvt_pk_bf16_f32 v82, v12, v13
	v_lshlrev_b32_e32 v12, 16, v83
	v_and_b32_e32 v13, 0xffff0000, v83
	v_mul_f32_e32 v12, 0x3e16c740, v12
	v_mul_f32_e32 v13, 0x3e16c740, v13
	v_cvt_pk_bf16_f32 v83, v12, v13
	v_lshlrev_b32_e32 v12, 16, v84
	v_and_b32_e32 v13, 0xffff0000, v84
	v_mul_f32_e32 v12, 0x3e16c740, v12
	v_mul_f32_e32 v13, 0x3e16c740, v13
	v_cvt_pk_bf16_f32 v84, v12, v13
	v_lshlrev_b32_e32 v12, 16, v85
	v_and_b32_e32 v13, 0xffff0000, v85
	v_mul_f32_e32 v12, 0x3e16c740, v12
	v_mul_f32_e32 v13, 0x3e16c740, v13
	v_cvt_pk_bf16_f32 v85, v12, v13
	v_lshlrev_b32_e32 v12, 16, v86
	v_and_b32_e32 v13, 0xffff0000, v86
	v_mul_f32_e32 v12, 0x3e16c740, v12
	v_mul_f32_e32 v13, 0x3e16c740, v13
	v_cvt_pk_bf16_f32 v86, v12, v13
	v_lshlrev_b32_e32 v12, 16, v87
	v_and_b32_e32 v13, 0xffff0000, v87
	v_mul_f32_e32 v12, 0x3e16c740, v12
	v_mul_f32_e32 v13, 0x3e16c740, v13
	v_cvt_pk_bf16_f32 v87, v12, v13
	s_waitcnt lgkmcnt(0)
	s_barrier
; template <int DQK> __device__ __forceinline__ void partialSM(f32x16& p0, f32x16& p1, float& m_reg, float& mn, float& alpha) {
;   constexpr float SCALE = (DQK == 96) ? 0.10206207261596577f : 0.125f;
;   constexpr float C = SCALE * 1.4426950408889634f;
;   float pmax = p0[0];
; #pragma unroll
;   for (int r = 1; r < 16; ++r) pmax = fmaxf(pmax, p0[r]);
; #pragma unroll
;   for (int r = 0; r < 16; ++r) pmax = fmaxf(pmax, p1[r]);
;   { auto rr = __builtin_amdgcn_permlane32_swap(__float_as_uint(pmax), __float_as_uint(pmax), false, false);
;     pmax = fmaxf(__uint_as_float(rr[0]), __uint_as_float(rr[1])); }
;   if (__builtin_expect(__all(pmax - m_reg <= THR / SCALE), 1)) { mn = m_reg; alpha = 1.f; }
;   else { mn = fmaxf(m_reg, pmax); alpha = __builtin_amdgcn_exp2f((m_reg - mn) * C); m_reg = mn; }
;   float mnC = -mn * C;
; #pragma unroll
;   for (int r = 0; r < 16; ++r) p0[r] = fmaf(p0[r], C, mnC);
; #pragma unroll
;   for (int r = 0; r < 16; ++r) p1[r] = fmaf(p1[r], C, mnC);
; #pragma unroll
;   for (int r = 0; r < 16; ++r) p0[r] = __builtin_amdgcn_exp2f(p0[r]);
; template <int DQK> __device__ __forceinline__ void qkt(f32x16& p0, f32x16& p1, const char* Ks, const bf16x8* qr, int r32, int hi) {
;   p0 = f32x16{}; p1 = f32x16{};
; #pragma unroll
;   for (int d0 = 0; d0 < DQK / 16; ++d0) { int cb = (d0 * 16 + hi * 8) * 2;
;     bf16x8 b0 = *reinterpret_cast<const bf16x8*>(Ks + KSWZ(r32, cb));
;     bf16x8 b1 = *reinterpret_cast<const bf16x8*>(Ks + KSWZ(32 + r32, cb));
;     p0 = __builtin_amdgcn_mfma_f32_32x32x16_bf16(b0, qr[d0], p0, 0, 0, 0);
;     p1 = __builtin_amdgcn_mfma_f32_32x32x16_bf16(b1, qr[d0], p1, 0, 0, 0); }
	ds_read_b128 v[0:3], v148 offset:32768
	ds_read_b128 v[4:7], v148 offset:40960
	s_waitcnt lgkmcnt(1)
	v_mfma_f32_32x32x16_bf16 v[32:47], v[0:3], v[84:87], 0
	v_or_b32_e32 v0, 32, v204
	v_bitop3_b32 v0, v0, v8, v9 bitop3:0xde
	v_add_u32_e32 v152, 0, v0
	v_lshlrev_b32_e32 v10, 3, v56
	v_and_b32_e32 v11, 0xc0, v53
	s_mov_b32 s89, s77
	s_mov_b32 s90, s77
	s_waitcnt lgkmcnt(0)
	v_mfma_f32_32x32x16_bf16 v[16:31], v[4:7], v[84:87], 0
	ds_read_b128 v[0:3], v152 offset:32768
	ds_read_b128 v[4:7], v152 offset:40960
	s_mov_b32 s91, s77
	v_lshl_add_u64 v[134:135], s[4:5], 0, v[48:49]
	v_lshl_add_u64 v[136:137], s[0:1], 0, v[48:49]
	s_mov_b32 s13, s77
	s_mov_b32 s11, 4
	v_lshl_add_u64 v[138:139], s[0:1], 0, v[50:51]
	s_sub_u32 s98, s0, s18
	s_sub_u32 s99, s4, s20
	v_mad_u32_u24 v134, v130, s70, v48
	v_lshl_add_u32 v135, v130, 9, v48
	v_mad_u32_u24 v238, v132, s70, v50
	v_add_u32_e32 v134, s98, v134
	v_add_u32_e32 v135, s99, v135
	v_add_u32_e32 v238, s98, v238
	s_waitcnt lgkmcnt(1)
	v_mfma_f32_32x32x16_bf16 v[32:47], v[0:3], v[80:83], v[32:47]
	v_or_b32_e32 v0, 64, v204
	v_bitop3_b32 v0, v0, v8, v9 bitop3:0xde
	v_add_u32_e32 v151, 0, v0
	v_cmp_gt_u32_e64 s[4:5], 32, v56
	v_mov_b32_e32 v142, 0
	s_waitcnt lgkmcnt(0)
	v_mfma_f32_32x32x16_bf16 v[16:31], v[4:7], v[80:83], v[16:31]
	ds_read_b128 v[0:3], v151 offset:32768
	ds_read_b128 v[4:7], v151 offset:40960
	s_waitcnt lgkmcnt(1)
	v_mfma_f32_32x32x16_bf16 v[32:47], v[0:3], v[76:79], v[32:47]
	v_or_b32_e32 v0, 0x60, v204
	v_bitop3_b32 v0, v0, v8, v9 bitop3:0xde
	v_add_u32_e32 v149, 0, v0
	ds_read_b128 v[0:3], v149 offset:32768
	s_waitcnt lgkmcnt(1)
	v_mfma_f32_32x32x16_bf16 v[16:31], v[4:7], v[76:79], v[16:31]
	v_and_b32_e32 v4, 0x3fffffc0, v52
	v_lshl_add_u32 v57, v4, 2, s26
	ds_read_b128 v[4:7], v149 offset:40960
	v_lshl_add_u32 v141, v140, 2, v57
	v_add_u32_e32 v129, v57, v204
	s_waitcnt lgkmcnt(1)
	v_mfma_f32_32x32x16_bf16 v[32:47], v[0:3], v[72:75], v[32:47]
	v_or_b32_e32 v0, 0x80, v204
	v_bitop3_b32 v0, v0, v8, v9 bitop3:0xde
	v_add_u32_e32 v150, 0, v0
	ds_read_b128 v[0:3], v150 offset:32768
	s_waitcnt lgkmcnt(1)
	v_mfma_f32_32x32x16_bf16 v[16:31], v[4:7], v[72:75], v[16:31]
	v_lshlrev_b32_e32 v5, 1, v52
	v_and_or_b32 v4, v10, 24, v11
	v_and_b32_e32 v5, 32, v5
	v_and_b32_e32 v6, 0x100, v10
	v_or3_b32 v58, v4, v5, v6
	ds_read_b128 v[4:7], v150 offset:40960
	v_add_u32_e32 v144, s25, v58
	s_waitcnt lgkmcnt(1)
	v_mfma_f32_32x32x16_bf16 v[32:47], v[0:3], v[68:71], v[32:47]
	v_or_b32_e32 v0, 0xa0, v204
	v_bitop3_b32 v0, v0, v8, v9 bitop3:0xde
	v_add_u32_e32 v153, 0, v0
	ds_read_b128 v[0:3], v153 offset:32768
	ds_read_b128 v[52:55], v153 offset:40960
	v_writelane_b32 v255, s12, 19
	s_waitcnt lgkmcnt(2)
	v_mfma_f32_32x32x16_bf16 v[16:31], v[4:7], v[68:71], v[16:31]
	v_writelane_b32 v255, s13, 20
	v_writelane_b32 v255, s14, 21
	v_writelane_b32 v255, s15, 22
	v_writelane_b32 v255, s16, 23
	v_writelane_b32 v255, s17, 24
	v_writelane_b32 v255, s18, 25
	v_writelane_b32 v255, s19, 26
	s_waitcnt lgkmcnt(1)
	v_mfma_f32_32x32x16_bf16 v[32:47], v[0:3], v[64:67], v[32:47]
	v_mov_b64_e32 v[0:1], s[76:77]
	v_mov_b64_e32 v[2:3], s[78:79]
	v_mov_b64_e32 v[4:5], s[80:81]
	v_mov_b64_e32 v[6:7], s[82:83]
	v_mov_b64_e32 v[8:9], s[84:85]
	v_mov_b64_e32 v[10:11], s[86:87]
	v_mov_b64_e32 v[12:13], s[88:89]
	s_waitcnt lgkmcnt(0)
	v_mfma_f32_32x32x16_bf16 v[16:31], v[52:55], v[64:67], v[16:31]
	s_nop 2
	v_max_f32_e32 v52, v33, v33
	v_max_f32_e32 v53, v32, v32
	v_max_f32_e32 v52, v53, v52
	v_max3_f32 v52, v52, v34, v35
	v_max3_f32 v52, v52, v36, v37
	v_max3_f32 v52, v52, v38, v39
	v_max3_f32 v52, v52, v40, v41
	v_max3_f32 v52, v52, v42, v43
	v_max3_f32 v52, v52, v44, v45
	v_max3_f32 v52, v52, v46, v47
	v_max3_f32 v52, v52, v16, v17
	v_max3_f32 v52, v52, v18, v19
	v_max3_f32 v52, v52, v20, v21
	v_max3_f32 v52, v52, v22, v23
	v_max3_f32 v52, v52, v24, v25
	v_max3_f32 v52, v52, v26, v27
	v_max3_f32 v52, v52, v28, v29
	v_max3_f32 v52, v52, v30, v31
	v_mov_b32_e32 v53, v52
	s_nop 1
	v_permlane32_swap_b32_e32 v52, v53
	v_max_f32_e32 v53, v53, v53
	v_max_f32_e32 v52, v52, v52
	v_max_f32_e32 v52, v52, v53
	v_mov_b64_e32 v[14:15], s[90:91]
	s_mov_b32 s80, 0x4138aa3b
	v_add_f32_e32 v53, 0x7149f2ca, v52
	v_cmp_ge_f32_e32 vcc, s80, v53
	s_cmp_eq_u64 vcc, exec
	v_max_f32_e32 v49, 0xf149f2ca, v52
	s_cselect_b64 vcc, -1, 0
	v_cndmask_b32_e32 v116, v49, v248, vcc
	v_mul_f32_e32 v48, 0xbf800000, v116
	v_fmamk_f32 v32, v32, 0x3f800000, v48
	v_exp_f32_e32 v126, v32
	v_fmamk_f32 v32, v33, 0x3f800000, v48
	v_exp_f32_e32 v160, v32
	v_fmamk_f32 v32, v34, 0x3f800000, v48
	v_exp_f32_e32 v127, v32
	v_fmamk_f32 v32, v35, 0x3f800000, v48
	v_exp_f32_e32 v161, v32
	v_fmamk_f32 v32, v36, 0x3f800000, v48
	v_exp_f32_e32 v158, v32
	v_fmamk_f32 v32, v37, 0x3f800000, v48
	v_exp_f32_e32 v162, v32
	v_fmamk_f32 v32, v38, 0x3f800000, v48
	v_exp_f32_e32 v159, v32
	v_fmamk_f32 v32, v39, 0x3f800000, v48
	v_writelane_b32 v255, s20, 27
	v_exp_f32_e32 v163, v32
	v_fmamk_f32 v32, v40, 0x3f800000, v48
	v_writelane_b32 v255, s21, 28
	v_exp_f32_e32 v118, v32
	v_fmamk_f32 v32, v41, 0x3f800000, v48
	v_writelane_b32 v255, s22, 29
	v_exp_f32_e32 v121, v32
	v_fmamk_f32 v32, v42, 0x3f800000, v48
	v_sub_f32_e32 v33, 0xf149f2ca, v49
	v_writelane_b32 v255, s23, 30
	v_exp_f32_e32 v119, v32
	v_fmamk_f32 v32, v43, 0x3f800000, v48
	v_mul_f32_e32 v33, 0x3f800000, v33
	v_writelane_b32 v255, s24, 31
	v_exp_f32_e32 v122, v32
	v_fmamk_f32 v32, v44, 0x3f800000, v48
	v_exp_f32_e32 v33, v33
	v_writelane_b32 v255, s25, 32
	v_exp_f32_e32 v120, v32
	v_fmamk_f32 v32, v45, 0x3f800000, v48
	v_writelane_b32 v255, s26, 33
	v_exp_f32_e32 v123, v32
	v_fmamk_f32 v32, v46, 0x3f800000, v48
	v_writelane_b32 v255, s27, 34
; #define SBAR() __builtin_amdgcn_sched_barrier(0)
; #define BIAS(P0, P1, j) do { if (MODE == 1) { SBAR(); if ((j) >= nA) na_bias(P0, P1, na, rs0 + (j) - nA, hi); SBAR(); } } while (0)
; template <int DQK> __device__ __forceinline__ void partialSM(f32x16& p0, f32x16& p1, float& m_reg, float& mn, float& alpha) {
;     ...
;   if (__builtin_expect(__all(pmax - m_reg <= THR / SCALE), 1)) { mn = m_reg; alpha = 1.f; }
;   else { mn = fmaxf(m_reg, pmax); alpha = __builtin_amdgcn_exp2f((m_reg - mn) * C); m_reg = mn; }
;   float mnC = -mn * C;
; #pragma unroll
;   for (int r = 0; r < 16; ++r) p0[r] = fmaf(p0[r], C, mnC);
; #pragma unroll
;   for (int r = 0; r < 16; ++r) p1[r] = fmaf(p1[r], C, mnC);
; #pragma unroll
;   for (int r = 0; r < 16; ++r) p0[r] = __builtin_amdgcn_exp2f(p0[r]);
; template <int DQK, int MODE, int ldq, int ldk, int ldv> ...
;     ...
;   __syncthreads();
;   qkt<DQK>(pA0, pA1, K_lds, qr, r32, hi); BIAS(pA0, pA1, 0); partialSM<DQK>(pA0, pA1, m_reg, mnA, alA);
;   for (int j = 1; j + 1 < NT; j += 2) {
;     SBAR(); qkt<DQK>(pB0, pB1, K_lds + SHM_K, qr, r32, hi);
	v_exp_f32_e32 v124, v32
	v_fmamk_f32 v32, v47, 0x3f800000, v48
	v_fmamk_f32 v100, v30, 0x3f800000, v48
	v_fmamk_f32 v101, v31, 0x3f800000, v48
	v_fmamk_f32 v106, v28, 0x3f800000, v48
	v_fmamk_f32 v107, v29, 0x3f800000, v48
	v_fmamk_f32 v110, v26, 0x3f800000, v48
	v_fmamk_f32 v111, v27, 0x3f800000, v48
	v_fmamk_f32 v102, v24, 0x3f800000, v48
	v_fmamk_f32 v103, v25, 0x3f800000, v48
	v_fmamk_f32 v104, v22, 0x3f800000, v48
	v_fmamk_f32 v105, v23, 0x3f800000, v48
	v_fmamk_f32 v108, v20, 0x3f800000, v48
	v_fmamk_f32 v109, v21, 0x3f800000, v48
	v_fmamk_f32 v112, v18, 0x3f800000, v48
	v_fmamk_f32 v113, v19, 0x3f800000, v48
	v_fmamk_f32 v114, v16, 0x3f800000, v48
	v_fmamk_f32 v115, v17, 0x3f800000, v48
	s_addk_i32 s25, 0x4000
	v_mov_b64_e32 v[30:31], v[14:15]
	s_mov_b64 s[84:85], 0x90000
	s_movk_i32 s83, 0x6000
	s_movk_i32 s82, 0x100
	v_readlane_b32 s89, v255, 47
	v_readlane_b32 s76, v255, 37
	s_movk_i32 s90, 0x1fff
	s_mov_b32 s88, 0x42800000
	s_movk_i32 s87, 0x7000
	s_movk_i32 s86, 0x1200
	s_movk_i32 s81, 0x5000
	s_movk_i32 s78, 0x4000
	v_exp_f32_e32 v125, v32
	v_cndmask_b32_e64 v154, v33, 1.0, vcc
	v_add_u32_e32 v143, s25, v58
	v_mov_b64_e32 v[28:29], v[12:13]
	v_mov_b64_e32 v[26:27], v[10:11]
	v_mov_b64_e32 v[24:25], v[8:9]
	v_mov_b64_e32 v[22:23], v[6:7]
	v_mov_b64_e32 v[20:21], v[4:5]
	v_mov_b64_e32 v[18:19], v[2:3]
	v_mov_b64_e32 v[16:17], v[0:1]
	v_exp_f32_e32 v114, v114
	v_exp_f32_e32 v115, v115
	v_exp_f32_e32 v112, v112
	v_exp_f32_e32 v113, v113
	v_exp_f32_e32 v108, v108
	v_exp_f32_e32 v109, v109
	v_exp_f32_e32 v104, v104
	v_exp_f32_e32 v105, v105
	v_exp_f32_e32 v102, v102
	v_exp_f32_e32 v103, v103
	v_exp_f32_e32 v110, v110
	v_exp_f32_e32 v111, v111
	v_exp_f32_e32 v106, v106
	v_exp_f32_e32 v107, v107
	v_exp_f32_e32 v101, v101
	v_exp_f32_e32 v100, v100
	v_sub_f32_e32 v210, 0, v116
	v_mov_b32_e32 v211, v210
	v_mov_b32_e32 v212, v210
	v_mov_b32_e32 v213, v210
	v_mov_b32_e32 v214, v210
	v_mov_b32_e32 v215, v210
	v_mov_b32_e32 v216, v210
	v_mov_b32_e32 v217, v210
	v_mov_b32_e32 v218, v210
	v_mov_b32_e32 v219, v210
	v_mov_b32_e32 v220, v210
	v_mov_b32_e32 v221, v210
	v_mov_b32_e32 v222, v210
	v_mov_b32_e32 v223, v210
	v_mov_b32_e32 v224, v210
	v_mov_b32_e32 v225, v210
	s_barrier
	.p2align 8
; #define SBAR() __builtin_amdgcn_sched_barrier(0)
; #define SLOAD(i, j) do { const long kr_ = KROW(j); sr_[i].vs0 = ld8(Vp + (kr_ + sr) * ldv + sc); sr_[i].ks0 = ld8(Kp + (kr_ + sr) * ldk + sc); \
;     if (DQK == 96) sr_[i].ks1 = ld8(Kp + (kr_ + sr2) * ldk + sc2); } while (0)
; #define BIAS(P0, P1, j) do { if (MODE == 1) { SBAR(); if ((j) >= nA) na_bias(P0, P1, na, rs0 + (j) - nA, hi); SBAR(); } } while (0)
; __device__ __forceinline__ void finishSM(f32x16& p0, f32x16& p1, float alpha, float& l_reg, bf16x8& pa0, bf16x8& pa1, bf16x8& pa2, bf16x8& pa3) {
;     ...
;   PK4(p0, 0, pa0); PK4(p0, 8, pa1); PK4(p1, 0, pa2); PK4(p1, 8, pa3);
; template <int DQK, int MODE, int ldq, int ldk, int ldv> ...
;     ...
;   for (int j = 1; j + 1 < NT; j += 2) {
;     SBAR(); qkt<DQK>(pB0, pB1, K_lds + SHM_K, qr, r32, hi);
;     finishSM(pA0, pA1, alA, l_reg, pa0, pa1, pa2, pa3); SBAR();
;     SLOAD(SO, j + 2); SBAR();
;     pv_d0(o, vb0, pa0, pa1, pa2, pa3); BIAS(pB0, pB1, j); partialSM<DQK>(pB0, pB1, m_reg, mnB, alB);
.LBB0_300:
	s_add_i32 s25, s11, -3
	s_cmp_lg_u32 s32, 0
	s_cbranch_scc1 .Lmy_h1B
	ds_read_b128 v[32:35], v148 offset:49152
	ds_read_b128 v[36:39], v148 offset:57344
	ds_read_b128 v[164:167], v152 offset:49152
	ds_read_b128 v[168:171], v152 offset:57344
	s_waitcnt lgkmcnt(3)
	v_mfma_f32_32x32x16_bf16 v[48:63], v[32:35], v[84:87], v[210:225]
	s_waitcnt lgkmcnt(2)
	v_mfma_f32_32x32x16_bf16 v[32:47], v[36:39], v[84:87], v[210:225]
	s_waitcnt lgkmcnt(1)
	v_mfma_f32_32x32x16_bf16 v[48:63], v[164:167], v[80:83], v[48:63]
	s_waitcnt lgkmcnt(0)
	v_mfma_f32_32x32x16_bf16 v[32:47], v[168:171], v[80:83], v[32:47]
	ds_read_b128 v[164:167], v151 offset:49152
	ds_read_b128 v[168:171], v151 offset:57344
	s_waitcnt lgkmcnt(1)
	v_mfma_f32_32x32x16_bf16 v[48:63], v[164:167], v[76:79], v[48:63]
	s_waitcnt lgkmcnt(0)
	v_mfma_f32_32x32x16_bf16 v[32:47], v[168:171], v[76:79], v[32:47]
	ds_read_b128 v[164:167], v149 offset:49152
	ds_read_b128 v[168:171], v149 offset:57344
	s_waitcnt lgkmcnt(1)
	v_mfma_f32_32x32x16_bf16 v[48:63], v[164:167], v[72:75], v[48:63]
	s_waitcnt lgkmcnt(0)
	v_mfma_f32_32x32x16_bf16 v[32:47], v[168:171], v[72:75], v[32:47]
	ds_read_b128 v[164:167], v150 offset:49152
	ds_read_b128 v[168:171], v150 offset:57344
	s_waitcnt lgkmcnt(1)
	v_mfma_f32_32x32x16_bf16 v[48:63], v[164:167], v[68:71], v[48:63]
	s_waitcnt lgkmcnt(0)
	v_mfma_f32_32x32x16_bf16 v[32:47], v[168:171], v[68:71], v[32:47]
	ds_read_b128 v[164:167], v153 offset:49152
	ds_read_b128 v[168:171], v153 offset:57344
	s_waitcnt vmcnt(0)
	ds_write_b128 v146, v[88:91] offset:32768
	ds_write_b128 v147, v[96:99] offset:32768
	ds_write_b128 v145, v[92:95] offset:16384
	s_waitcnt lgkmcnt(4)
	v_mfma_f32_32x32x16_bf16 v[48:63], v[164:167], v[64:67], v[48:63]
	s_waitcnt lgkmcnt(3)
	v_mfma_f32_32x32x16_bf16 v[32:47], v[168:171], v[64:67], v[32:47]
	ds_read_b64_tr_b16 v[184:185], v144 offset:0
	ds_read_b64_tr_b16 v[186:187], v144 offset:0x800
	ds_read_b64_tr_b16 v[188:189], v144 offset:0x1000
	ds_read_b64_tr_b16 v[190:191], v144 offset:0x1800
	ds_read_b64_tr_b16 v[192:193], v144 offset:0x2000
	ds_read_b64_tr_b16 v[194:195], v144 offset:0x2800
	ds_read_b64_tr_b16 v[196:197], v144 offset:0x3000
	ds_read_b64_tr_b16 v[198:199], v144 offset:0x3800
	v_mov_b32_e32 v117, v114
	v_mov_b32_e32 v157, v115
	v_mov_b32_e32 v164, v112
	v_add_f32_e32 v112, 0, v126
	v_add_f32_e32 v112, v160, v112
	v_add_f32_e32 v112, v127, v112
	v_add_f32_e32 v112, v161, v112
	v_add_f32_e32 v112, v158, v112
	v_add_f32_e32 v112, v162, v112
	v_add_f32_e32 v112, v159, v112
	v_add_f32_e32 v112, v163, v112
	v_add_f32_e32 v112, v118, v112
	v_add_f32_e32 v112, v121, v112
	v_add_f32_e32 v112, v119, v112
	v_add_f32_e32 v112, v122, v112
	v_add_f32_e32 v112, v120, v112
	v_add_f32_e32 v112, v123, v112
	v_add_f32_e32 v112, v124, v112
	v_mov_b32_e32 v165, v113
	v_add_f32_e32 v112, v125, v112
	v_add_f32_e32 v112, v117, v112
	v_add_f32_e32 v112, v157, v112
	v_add_f32_e32 v112, v164, v112
	v_add_f32_e32 v112, v165, v112
	v_add_f32_e32 v112, v108, v112
	v_add_f32_e32 v112, v109, v112
	v_add_f32_e32 v112, v104, v112
	v_add_f32_e32 v112, v105, v112
	v_add_f32_e32 v112, v102, v112
	v_add_f32_e32 v112, v103, v112
	v_add_f32_e32 v112, v110, v112
	v_add_f32_e32 v112, v111, v112
	v_add_f32_e32 v112, v106, v112
	v_add_f32_e32 v112, v107, v112
	v_add_f32_e32 v112, v100, v112
	v_add_f32_e32 v155, v101, v112
	v_mov_b32_e32 v156, v155
	v_cvt_pk_bf16_f32 v200, v126, v160
	v_cvt_pk_bf16_f32 v201, v127, v161
	v_cvt_pk_bf16_f32 v202, v158, v162
	s_nop 1
	v_permlane32_swap_b32_e32 v155, v156
	v_cvt_pk_bf16_f32 v203, v159, v163
	v_cvt_pk_bf16_f32 v226, v118, v121
	v_cvt_pk_bf16_f32 v227, v119, v122
	v_cvt_pk_bf16_f32 v228, v120, v123
	v_cvt_pk_bf16_f32 v229, v124, v125
	v_cvt_pk_bf16_f32 v230, v117, v157
	v_cvt_pk_bf16_f32 v231, v164, v165
	v_cvt_pk_bf16_f32 v232, v108, v109
	v_cvt_pk_bf16_f32 v233, v104, v105
	v_cvt_pk_bf16_f32 v136, v102, v103
	v_cvt_pk_bf16_f32 v137, v110, v111
	v_cvt_pk_bf16_f32 v138, v106, v107
	v_cvt_pk_bf16_f32 v139, v100, v101
	s_lshl_b32 s0, s11, 6
	s_cmpk_lt_u32 s25, 0x7e
	s_cselect_b32 s1, s10, s24
	s_add_i32 s1, s1, s0
	s_addk_i32 s1, 0xffc0
	s_mul_i32 s1, s1, 0x300
	s_add_u32 s12, s18, s1
	s_addc_u32 s13, s19, 0
	s_cmpk_lt_u32 s25, 0x7f
	s_cselect_b32 s98, s10, s24
	s_add_i32 s98, s98, s0
	s_addk_i32 s98, 0xff80
	s_lshl_b32 s98, s98, 9
	s_add_u32 s98, s20, s98
	s_addc_u32 s99, s21, 0
	global_load_dwordx4 v[100:103], v134, s[12:13]
	global_load_dwordx4 v[108:111], v135, s[98:99]
	global_load_dwordx4 v[104:107], v238, s[12:13] offset:128
	s_waitcnt lgkmcnt(0)
	s_nop 0
	v_mfma_f32_32x32x16_bf16 v[0:15], v[200:203], v[184:187], v[0:15]
	ds_read_b64_tr_b16 v[184:185], v144 offset:0x200
	ds_read_b64_tr_b16 v[186:187], v144 offset:0xa00
	v_max_f32_e32 v112, v48, v49
	v_max3_f32 v112, v112, v50, v51
	v_max3_f32 v112, v112, v52, v53
	v_max3_f32 v112, v112, v54, v55
	v_max3_f32 v112, v112, v56, v57
	v_mfma_f32_32x32x16_bf16 v[0:15], v[226:229], v[188:191], v[0:15]
	ds_read_b64_tr_b16 v[188:189], v144 offset:0x1200
	ds_read_b64_tr_b16 v[190:191], v144 offset:0x1a00
	v_max3_f32 v112, v112, v58, v59
	v_max3_f32 v112, v112, v60, v61
	v_max3_f32 v112, v112, v62, v63
	v_max3_f32 v112, v112, v32, v33
	v_max3_f32 v112, v112, v34, v35
	v_mfma_f32_32x32x16_bf16 v[0:15], v[230:233], v[192:195], v[0:15]
	ds_read_b64_tr_b16 v[192:193], v144 offset:0x2200
	ds_read_b64_tr_b16 v[194:195], v144 offset:0x2a00
	v_max3_f32 v112, v112, v36, v37
	v_max3_f32 v112, v112, v38, v39
	v_max3_f32 v112, v112, v40, v41
	v_max3_f32 v112, v112, v42, v43
	v_max3_f32 v112, v112, v44, v45
	v_mfma_f32_32x32x16_bf16 v[0:15], v[136:139], v[196:199], v[0:15]
	ds_read_b64_tr_b16 v[196:197], v144 offset:0x3200
	ds_read_b64_tr_b16 v[198:199], v144 offset:0x3a00
	v_max3_f32 v112, v112, v46, v47
	v_mov_b32_e32 v113, v112
	s_nop 1
	v_permlane32_swap_b32_e32 v112, v113
	v_max_f32_e32 v112, v112, v113
	v_cmp_ge_f32_e32 vcc, s80, v112
	s_cmp_eq_u64 vcc, exec
	s_cbranch_scc0 .Lmy_rare_a1
	v_mov_b32_e32 v157, 1.0

; #define SBAR() __builtin_amdgcn_sched_barrier(0)
; #define SLOAD(i, j) do { const long kr_ = KROW(j); sr_[i].vs0 = ld8(Vp + (kr_ + sr) * ldv + sc); sr_[i].ks0 = ld8(Kp + (kr_ + sr) * ldk + sc); \
;     if (DQK == 96) sr_[i].ks1 = ld8(Kp + (kr_ + sr2) * ldk + sc2); } while (0)
; __device__ __forceinline__ void finishSM(f32x16& p0, f32x16& p1, float alpha, float& l_reg, bf16x8& pa0, bf16x8& pa1, bf16x8& pa2, bf16x8& pa3) {
; #pragma unroll
;   for (int r = 0; r < 16; ++r) p1[r] = __builtin_amdgcn_exp2f(p1[r]);
;   float ps = 0;
; #pragma unroll
;   for (int r = 0; r < 16; ++r) ps += p0[r];
; #pragma unroll
;   for (int r = 0; r < 16; ++r) ps += p1[r];
;   { auto rr = __builtin_amdgcn_permlane32_swap(__float_as_uint(ps), __float_as_uint(ps), false, false);
;     ps = __uint_as_float(rr[0]) + __uint_as_float(rr[1]); }
;   l_reg = l_reg * alpha + ps;
;     ...
;   PK4(p0, 0, pa0); PK4(p0, 8, pa1); PK4(p1, 0, pa2); PK4(p1, 8, pa3);
; template <int DQK, int MODE, int ldq, int ldk, int ldv> ...
;     ...
;     SBAR(); qkt<DQK>(pA0, pA1, K_lds, qr, r32, hi);
;     finishSM(pB0, pB1, alB, l_reg, pa0, pa1, pa2, pa3); SBAR();
;     if (j + 3 < NT) SLOAD(SE, j + 3); SBAR();
.LBB0_304:
	s_waitcnt lgkmcnt(0)
	s_barrier
	ds_read_b128 v[32:35], v148 offset:32768
	ds_read_b128 v[36:39], v148 offset:40960
	ds_read_b128 v[176:179], v152 offset:32768
	ds_read_b128 v[180:183], v152 offset:40960
	s_waitcnt lgkmcnt(3)
	v_mfma_f32_32x32x16_bf16 v[48:63], v[32:35], v[84:87], v[210:225]
	s_waitcnt lgkmcnt(2)
	v_mfma_f32_32x32x16_bf16 v[32:47], v[36:39], v[84:87], v[210:225]
	s_waitcnt lgkmcnt(1)
	v_mfma_f32_32x32x16_bf16 v[48:63], v[176:179], v[80:83], v[48:63]
	s_waitcnt lgkmcnt(0)
	v_mfma_f32_32x32x16_bf16 v[32:47], v[180:183], v[80:83], v[32:47]
	ds_read_b128 v[176:179], v151 offset:32768
	ds_read_b128 v[180:183], v151 offset:40960
	s_waitcnt lgkmcnt(1)
	v_mfma_f32_32x32x16_bf16 v[48:63], v[176:179], v[76:79], v[48:63]
	s_waitcnt lgkmcnt(0)
	v_mfma_f32_32x32x16_bf16 v[32:47], v[180:183], v[76:79], v[32:47]
	ds_read_b128 v[176:179], v149 offset:32768
	ds_read_b128 v[180:183], v149 offset:40960
	s_waitcnt lgkmcnt(1)
	v_mfma_f32_32x32x16_bf16 v[48:63], v[176:179], v[72:75], v[48:63]
	s_waitcnt lgkmcnt(0)
	v_mfma_f32_32x32x16_bf16 v[32:47], v[180:183], v[72:75], v[32:47]
	ds_read_b128 v[176:179], v150 offset:32768
	ds_read_b128 v[180:183], v150 offset:40960
	s_waitcnt lgkmcnt(1)
	v_mfma_f32_32x32x16_bf16 v[48:63], v[176:179], v[68:71], v[48:63]
	s_waitcnt lgkmcnt(0)
	v_mfma_f32_32x32x16_bf16 v[32:47], v[180:183], v[68:71], v[32:47]
	ds_read_b128 v[176:179], v153 offset:32768
	ds_read_b128 v[180:183], v153 offset:40960
	s_waitcnt vmcnt(0)
	ds_write_b128 v146, v[100:103] offset:49152
	ds_write_b128 v147, v[104:107] offset:49152
	ds_write_b128 v145, v[108:111]
	s_waitcnt lgkmcnt(4)
	v_mfma_f32_32x32x16_bf16 v[48:63], v[176:179], v[64:67], v[48:63]
	s_waitcnt lgkmcnt(3)
	v_mfma_f32_32x32x16_bf16 v[32:47], v[180:183], v[64:67], v[32:47]
	ds_read_b64_tr_b16 v[184:185], v143 offset:0
	ds_read_b64_tr_b16 v[186:187], v143 offset:0x800
	ds_read_b64_tr_b16 v[188:189], v143 offset:0x1000
	ds_read_b64_tr_b16 v[190:191], v143 offset:0x1800
	ds_read_b64_tr_b16 v[192:193], v143 offset:0x2000
	ds_read_b64_tr_b16 v[194:195], v143 offset:0x2800
	ds_read_b64_tr_b16 v[196:197], v143 offset:0x3000
	ds_read_b64_tr_b16 v[198:199], v143 offset:0x3800
	v_mov_b32_e32 v175, v164
	v_add_f32_e32 v164, 0, v112
	v_add_f32_e32 v164, v127, v164
	v_add_f32_e32 v164, v113, v164
	v_add_f32_e32 v164, v126, v164
	v_add_f32_e32 v164, v114, v164
	v_add_f32_e32 v164, v125, v164
	v_add_f32_e32 v164, v115, v164
	v_add_f32_e32 v164, v124, v164
	v_add_f32_e32 v164, v116, v164
	v_add_f32_e32 v164, v123, v164
	v_add_f32_e32 v164, v117, v164
	v_add_f32_e32 v164, v122, v164
	v_add_f32_e32 v164, v118, v164
	v_add_f32_e32 v164, v121, v164
	v_add_f32_e32 v164, v119, v164
	v_add_f32_e32 v164, v120, v164
	v_add_f32_e32 v164, v167, v164
	v_add_f32_e32 v164, v168, v164
	v_add_f32_e32 v164, v169, v164
	v_add_f32_e32 v164, v170, v164
	v_add_f32_e32 v164, v171, v164
	v_add_f32_e32 v164, v172, v164
	v_add_f32_e32 v164, v160, v164
	v_add_f32_e32 v164, v161, v164
	v_add_f32_e32 v164, v162, v164
	v_add_f32_e32 v164, v163, v164
	v_add_f32_e32 v164, v175, v164
	v_cvt_pk_bf16_f32 v200, v112, v127
	v_cvt_pk_bf16_f32 v201, v113, v126
	v_cvt_pk_bf16_f32 v202, v114, v125
	v_cvt_pk_bf16_f32 v203, v115, v124
	v_cvt_pk_bf16_f32 v226, v116, v123
	v_cvt_pk_bf16_f32 v227, v117, v122
	v_mov_b32_e32 v176, v165
	v_cvt_pk_bf16_f32 v228, v118, v121
	v_cvt_pk_bf16_f32 v229, v119, v120
	v_cvt_pk_bf16_f32 v230, v167, v168
	v_cvt_pk_bf16_f32 v231, v169, v170
	v_cvt_pk_bf16_f32 v232, v171, v172
	s_nop 0
	v_add_f32_e32 v164, v176, v164
	v_add_f32_e32 v164, v166, v164
	v_add_f32_e32 v164, v173, v164
	v_add_f32_e32 v164, v174, v164
	v_add_f32_e32 v164, v159, v164
	v_mov_b32_e32 v165, v164
	v_cvt_pk_bf16_f32 v233, v160, v161
	v_cvt_pk_bf16_f32 v136, v162, v163
	v_cvt_pk_bf16_f32 v137, v175, v176
	v_cvt_pk_bf16_f32 v138, v166, v173
	v_cvt_pk_bf16_f32 v139, v174, v159
	s_nop 1
	v_permlane32_swap_b32_e32 v164, v165
	s_lshl_b32 s0, s11, 6
	s_cmpk_lt_u32 s25, 0x7e
	s_cselect_b32 s98, s10, s24
	s_add_i32 s98, s98, s0
	s_addk_i32 s98, 0xffc0
	s_lshl_b32 s98, s98, 9
	s_add_u32 s98, s20, s98
	s_addc_u32 s99, s21, 0
	global_load_dwordx4 v[92:95], v135, s[98:99]
	s_cmpk_gt_u32 s25, 0x80
	s_cbranch_scc1 .LBB0_306
	s_cmpk_lt_u32 s25, 0x7d
	s_cselect_b32 s1, s10, s24
	s_add_i32 s1, s1, s0
	s_mul_i32 s1, s1, 0x300
	s_add_u32 s12, s18, s1
	s_addc_u32 s13, s19, 0
	global_load_dwordx4 v[88:91], v134, s[12:13]
	global_load_dwordx4 v[96:99], v238, s[12:13] offset:128

; __device__ __forceinline__ void finishSM(f32x16& p0, f32x16& p1, float alpha, float& l_reg, bf16x8& pa0, bf16x8& pa1, bf16x8& pa2, bf16x8& pa3) {
; #pragma unroll
;   for (int r = 0; r < 16; ++r) p1[r] = __builtin_amdgcn_exp2f(p1[r]);
;   float ps = 0;
; #pragma unroll
;   for (int r = 0; r < 16; ++r) ps += p0[r];
; #pragma unroll
;   for (int r = 0; r < 16; ++r) ps += p1[r];
;   { auto rr = __builtin_amdgcn_permlane32_swap(__float_as_uint(ps), __float_as_uint(ps), false, false);
;     ps = __uint_as_float(rr[0]) + __uint_as_float(rr[1]); }
;   l_reg = l_reg * alpha + ps;
;     ...
;   PK4(p0, 0, pa0); PK4(p0, 8, pa1); PK4(p1, 0, pa2); PK4(p1, 8, pa3);
; template <int DQK> __device__ __forceinline__ void qkt(f32x16& p0, f32x16& p1, const char* Ks, const bf16x8* qr, int r32, int hi) {
;   p0 = f32x16{}; p1 = f32x16{};
; #pragma unroll
;   for (int d0 = 0; d0 < DQK / 16; ++d0) { int cb = (d0 * 16 + hi * 8) * 2;
;     bf16x8 b0 = *reinterpret_cast<const bf16x8*>(Ks + KSWZ(r32, cb));
;     bf16x8 b1 = *reinterpret_cast<const bf16x8*>(Ks + KSWZ(32 + r32, cb));
;     p0 = __builtin_amdgcn_mfma_f32_32x32x16_bf16(b0, qr[d0], p0, 0, 0, 0);
;     p1 = __builtin_amdgcn_mfma_f32_32x32x16_bf16(b1, qr[d0], p1, 0, 0, 0); }
; }
.Lmy_h1B:
	s_waitcnt vmcnt(0)
	ds_write_b128 v146, v[88:91] offset:32768
	ds_write_b128 v145, v[92:95] offset:16384
	v_mov_b32_e32 v117, v114
	v_mov_b32_e32 v157, v115
	v_mov_b32_e32 v164, v112
	v_add_f32_e32 v112, 0, v126
	v_add_f32_e32 v112, v160, v112
	v_add_f32_e32 v112, v127, v112
	v_add_f32_e32 v112, v161, v112
	v_add_f32_e32 v112, v158, v112
	v_add_f32_e32 v112, v162, v112
	v_add_f32_e32 v112, v159, v112
	v_add_f32_e32 v112, v163, v112
	v_add_f32_e32 v112, v118, v112
	v_add_f32_e32 v112, v121, v112
	v_add_f32_e32 v112, v119, v112
	v_add_f32_e32 v112, v122, v112
	v_add_f32_e32 v112, v120, v112
	v_add_f32_e32 v112, v123, v112
	v_add_f32_e32 v112, v124, v112
	v_mov_b32_e32 v165, v113
	v_add_f32_e32 v112, v125, v112
	v_add_f32_e32 v112, v117, v112
	v_add_f32_e32 v112, v157, v112
	v_add_f32_e32 v112, v164, v112
	v_add_f32_e32 v112, v165, v112
	v_add_f32_e32 v112, v108, v112
	v_add_f32_e32 v112, v109, v112
	v_add_f32_e32 v112, v104, v112
	v_add_f32_e32 v112, v105, v112
	v_add_f32_e32 v112, v102, v112
	v_add_f32_e32 v112, v103, v112
	v_add_f32_e32 v112, v110, v112
	v_add_f32_e32 v112, v111, v112
	v_add_f32_e32 v112, v106, v112
	v_add_f32_e32 v112, v107, v112
	v_add_f32_e32 v112, v100, v112
	v_add_f32_e32 v155, v101, v112
	v_mov_b32_e32 v156, v155
	v_cvt_pk_bf16_f32 v200, v126, v160
	v_cvt_pk_bf16_f32 v201, v127, v161
	v_cvt_pk_bf16_f32 v202, v158, v162
	s_nop 1
	v_permlane32_swap_b32_e32 v155, v156
	v_cvt_pk_bf16_f32 v203, v159, v163
	v_cvt_pk_bf16_f32 v226, v118, v121
	v_cvt_pk_bf16_f32 v227, v119, v122
	v_cvt_pk_bf16_f32 v228, v120, v123
	v_cvt_pk_bf16_f32 v229, v124, v125
	v_cvt_pk_bf16_f32 v230, v117, v157
	v_cvt_pk_bf16_f32 v231, v164, v165
	v_cvt_pk_bf16_f32 v232, v108, v109
	v_cvt_pk_bf16_f32 v233, v104, v105
	v_cvt_pk_bf16_f32 v136, v102, v103
	v_cvt_pk_bf16_f32 v137, v110, v111
	v_cvt_pk_bf16_f32 v138, v106, v107
	v_cvt_pk_bf16_f32 v139, v100, v101
	s_lshl_b32 s0, s11, 6
	s_cmpk_lt_u32 s25, 0x7e
	s_cselect_b32 s1, s10, s24
	s_add_i32 s1, s1, s0
	s_addk_i32 s1, 0xffc0
	s_mul_i32 s1, s1, 0x300
	s_add_u32 s12, s18, s1
	s_addc_u32 s13, s19, 0
	s_cmpk_lt_u32 s25, 0x7f
	s_cselect_b32 s98, s10, s24
	s_add_i32 s98, s98, s0
	s_addk_i32 s98, 0xff80
	s_lshl_b32 s98, s98, 9
	s_add_u32 s98, s20, s98
	s_addc_u32 s99, s21, 0
	global_load_dwordx4 v[100:103], v134, s[12:13]
	global_load_dwordx4 v[108:111], v135, s[98:99]
	ds_read_b64_tr_b16 v[184:185], v144 offset:0
	ds_read_b64_tr_b16 v[186:187], v144 offset:0x800
	ds_read_b64_tr_b16 v[188:189], v144 offset:0x1000
	ds_read_b64_tr_b16 v[190:191], v144 offset:0x1800
	ds_read_b64_tr_b16 v[192:193], v144 offset:0x2000
	ds_read_b64_tr_b16 v[194:195], v144 offset:0x2800
	ds_read_b64_tr_b16 v[196:197], v144 offset:0x3000
	ds_read_b64_tr_b16 v[198:199], v144 offset:0x3800
	s_waitcnt lgkmcnt(0)
	s_nop 0
	v_mfma_f32_32x32x16_bf16 v[0:15], v[200:203], v[184:187], v[0:15]
	ds_read_b64_tr_b16 v[184:185], v144 offset:0x200
	ds_read_b64_tr_b16 v[186:187], v144 offset:0xa00
	v_mfma_f32_32x32x16_bf16 v[0:15], v[226:229], v[188:191], v[0:15]
	ds_read_b64_tr_b16 v[188:189], v144 offset:0x1200
	ds_read_b64_tr_b16 v[190:191], v144 offset:0x1a00
	v_mfma_f32_32x32x16_bf16 v[0:15], v[230:233], v[192:195], v[0:15]
	ds_read_b64_tr_b16 v[192:193], v144 offset:0x2200
	ds_read_b64_tr_b16 v[194:195], v144 offset:0x2a00
	v_mfma_f32_32x32x16_bf16 v[0:15], v[136:139], v[196:199], v[0:15]
	ds_read_b64_tr_b16 v[196:197], v144 offset:0x3200
	ds_read_b64_tr_b16 v[198:199], v144 offset:0x3a00
	s_waitcnt lgkmcnt(0)
	v_mfma_f32_32x32x16_bf16 v[16:31], v[200:203], v[184:187], v[16:31]
	v_mfma_f32_32x32x16_bf16 v[16:31], v[226:229], v[188:191], v[16:31]
	v_mfma_f32_32x32x16_bf16 v[16:31], v[230:233], v[192:195], v[16:31]
	v_mfma_f32_32x32x16_bf16 v[16:31], v[136:139], v[196:199], v[16:31]
	ds_read_b128 v[32:35], v148 offset:49152
	ds_read_b128 v[36:39], v148 offset:57344
	ds_read_b128 v[164:167], v152 offset:49152
	ds_read_b128 v[168:171], v152 offset:57344
	s_waitcnt lgkmcnt(3)
	v_mfma_f32_32x32x16_bf16 v[48:63], v[32:35], v[84:87], v[210:225]
	s_waitcnt lgkmcnt(2)
	v_mfma_f32_32x32x16_bf16 v[32:47], v[36:39], v[84:87], v[210:225]
	s_waitcnt lgkmcnt(1)
	v_mfma_f32_32x32x16_bf16 v[48:63], v[164:167], v[80:83], v[48:63]
	s_waitcnt lgkmcnt(0)
	v_mfma_f32_32x32x16_bf16 v[32:47], v[168:171], v[80:83], v[32:47]
	ds_read_b128 v[164:167], v151 offset:49152
	ds_read_b128 v[168:171], v151 offset:57344
	s_waitcnt lgkmcnt(1)
	v_mfma_f32_32x32x16_bf16 v[48:63], v[164:167], v[76:79], v[48:63]
	s_waitcnt lgkmcnt(0)
	v_mfma_f32_32x32x16_bf16 v[32:47], v[168:171], v[76:79], v[32:47]
	ds_read_b128 v[164:167], v149 offset:49152
	ds_read_b128 v[168:171], v149 offset:57344
	s_waitcnt lgkmcnt(1)
	v_mfma_f32_32x32x16_bf16 v[48:63], v[164:167], v[72:75], v[48:63]
	s_waitcnt lgkmcnt(0)
	v_mfma_f32_32x32x16_bf16 v[32:47], v[168:171], v[72:75], v[32:47]
	ds_read_b128 v[164:167], v150 offset:49152
	ds_read_b128 v[168:171], v150 offset:57344
	s_waitcnt lgkmcnt(1)
	v_mfma_f32_32x32x16_bf16 v[48:63], v[164:167], v[68:71], v[48:63]
	s_waitcnt lgkmcnt(0)
	v_mfma_f32_32x32x16_bf16 v[32:47], v[168:171], v[68:71], v[32:47]
	ds_read_b128 v[164:167], v153 offset:49152
	ds_read_b128 v[168:171], v153 offset:57344
	s_waitcnt lgkmcnt(1)
	v_mfma_f32_32x32x16_bf16 v[48:63], v[164:167], v[64:67], v[48:63]
	s_waitcnt lgkmcnt(0)
	v_mfma_f32_32x32x16_bf16 v[32:47], v[168:171], v[64:67], v[32:47]
	s_nop 7
	s_nop 4
	v_max_f32_e32 v112, v48, v49
	v_max3_f32 v112, v112, v50, v51
	v_max3_f32 v112, v112, v52, v53
	v_max3_f32 v112, v112, v54, v55
	v_max3_f32 v112, v112, v56, v57
	v_max3_f32 v112, v112, v58, v59
	v_max3_f32 v112, v112, v60, v61
	v_max3_f32 v112, v112, v62, v63
	v_max3_f32 v112, v112, v32, v33
	v_max3_f32 v112, v112, v34, v35
	v_max3_f32 v112, v112, v36, v37
	v_max3_f32 v112, v112, v38, v39
	v_max3_f32 v112, v112, v40, v41
	v_max3_f32 v112, v112, v42, v43
	v_max3_f32 v112, v112, v44, v45
	v_max3_f32 v112, v112, v46, v47
	v_mov_b32_e32 v113, v112
	s_nop 1
	v_permlane32_swap_b32_e32 v112, v113
	v_max_f32_e32 v112, v112, v113
	v_cmp_ge_f32_e32 vcc, s80, v112
	s_cmp_eq_u64 vcc, exec
	s_cbranch_scc0 .Lmy_rare_b1
	v_mov_b32_e32 v157, 1.0

; #define SBAR() __builtin_amdgcn_sched_barrier(0)
; #define SLOAD(i, j) do { const long kr_ = KROW(j); sr_[i].vs0 = ld8(Vp + (kr_ + sr) * ldv + sc); sr_[i].ks0 = ld8(Kp + (kr_ + sr) * ldk + sc); \
;     if (DQK == 96) sr_[i].ks1 = ld8(Kp + (kr_ + sr2) * ldk + sc2); } while (0)
; __device__ __forceinline__ void finishSM(f32x16& p0, f32x16& p1, float alpha, float& l_reg, bf16x8& pa0, bf16x8& pa1, bf16x8& pa2, bf16x8& pa3) {
; #pragma unroll
;   for (int r = 0; r < 16; ++r) p1[r] = __builtin_amdgcn_exp2f(p1[r]);
;   float ps = 0;
; #pragma unroll
;   for (int r = 0; r < 16; ++r) ps += p0[r];
; #pragma unroll
;   for (int r = 0; r < 16; ++r) ps += p1[r];
;   { auto rr = __builtin_amdgcn_permlane32_swap(__float_as_uint(ps), __float_as_uint(ps), false, false);
;     ps = __uint_as_float(rr[0]) + __uint_as_float(rr[1]); }
;   l_reg = l_reg * alpha + ps;
;     ...
;   PK4(p0, 0, pa0); PK4(p0, 8, pa1); PK4(p1, 0, pa2); PK4(p1, 8, pa3);
; template <int DQK, int MODE, int ldq, int ldk, int ldv> ...
;     ...
;     SBAR(); qkt<DQK>(pA0, pA1, K_lds, qr, r32, hi);
;     finishSM(pB0, pB1, alB, l_reg, pa0, pa1, pa2, pa3); SBAR();
;     if (j + 3 < NT) SLOAD(SE, j + 3); SBAR();
.Lmy_h1B_304:
	s_waitcnt lgkmcnt(0)
	s_barrier
	s_waitcnt vmcnt(0)
	ds_write_b128 v146, v[100:103] offset:49152
	ds_write_b128 v145, v[108:111]
	v_mov_b32_e32 v175, v164
	v_add_f32_e32 v164, 0, v112
	v_add_f32_e32 v164, v127, v164
	v_add_f32_e32 v164, v113, v164
	v_add_f32_e32 v164, v126, v164
	v_add_f32_e32 v164, v114, v164
	v_add_f32_e32 v164, v125, v164
	v_add_f32_e32 v164, v115, v164
	v_add_f32_e32 v164, v124, v164
	v_add_f32_e32 v164, v116, v164
	v_add_f32_e32 v164, v123, v164
	v_add_f32_e32 v164, v117, v164
	v_add_f32_e32 v164, v122, v164
	v_add_f32_e32 v164, v118, v164
	v_add_f32_e32 v164, v121, v164
	v_add_f32_e32 v164, v119, v164
	v_add_f32_e32 v164, v120, v164
	v_add_f32_e32 v164, v167, v164
	v_add_f32_e32 v164, v168, v164
	v_add_f32_e32 v164, v169, v164
	v_add_f32_e32 v164, v170, v164
	v_add_f32_e32 v164, v171, v164
	v_add_f32_e32 v164, v172, v164
	v_add_f32_e32 v164, v160, v164
	v_add_f32_e32 v164, v161, v164
	v_add_f32_e32 v164, v162, v164
	v_add_f32_e32 v164, v163, v164
	v_add_f32_e32 v164, v175, v164
	v_cvt_pk_bf16_f32 v200, v112, v127
	v_cvt_pk_bf16_f32 v201, v113, v126
	v_cvt_pk_bf16_f32 v202, v114, v125
	v_cvt_pk_bf16_f32 v203, v115, v124
	v_cvt_pk_bf16_f32 v226, v116, v123
	v_cvt_pk_bf16_f32 v227, v117, v122
	v_mov_b32_e32 v176, v165
	v_cvt_pk_bf16_f32 v228, v118, v121
	v_cvt_pk_bf16_f32 v229, v119, v120
	v_cvt_pk_bf16_f32 v230, v167, v168
	v_cvt_pk_bf16_f32 v231, v169, v170
	v_cvt_pk_bf16_f32 v232, v171, v172
	s_nop 0
	v_add_f32_e32 v164, v176, v164
	v_add_f32_e32 v164, v166, v164
	v_add_f32_e32 v164, v173, v164
	v_add_f32_e32 v164, v174, v164
	v_add_f32_e32 v164, v159, v164
	v_mov_b32_e32 v165, v164
	v_cvt_pk_bf16_f32 v233, v160, v161
	v_cvt_pk_bf16_f32 v136, v162, v163
	v_cvt_pk_bf16_f32 v137, v175, v176
	v_cvt_pk_bf16_f32 v138, v166, v173
	v_cvt_pk_bf16_f32 v139, v174, v159
	s_nop 1
	v_permlane32_swap_b32_e32 v164, v165
	s_lshl_b32 s0, s11, 6
	s_cmpk_lt_u32 s25, 0x7e
	s_cselect_b32 s98, s10, s24
	s_add_i32 s98, s98, s0
	s_addk_i32 s98, 0xffc0
	s_lshl_b32 s98, s98, 9
	s_add_u32 s98, s20, s98
	s_addc_u32 s99, s21, 0
	global_load_dwordx4 v[92:95], v135, s[98:99]
	s_cmpk_gt_u32 s25, 0x80
	s_cbranch_scc1 .Lmy_h2B_306
	s_cmpk_lt_u32 s25, 0x7d
	s_cselect_b32 s1, s10, s24
	s_add_i32 s1, s1, s0
	s_mul_i32 s1, s1, 0x300
	s_add_u32 s12, s18, s1
	s_addc_u32 s13, s19, 0
	global_load_dwordx4 v[88:91], v134, s[12:13]

; #define SBAR() __builtin_amdgcn_sched_barrier(0)
; #define BIAS(P0, P1, j) do { if (MODE == 1) { SBAR(); if ((j) >= nA) na_bias(P0, P1, na, rs0 + (j) - nA, hi); SBAR(); } } while (0)
; template <int DQK> __device__ __forceinline__ void partialSM(f32x16& p0, f32x16& p1, float& m_reg, float& mn, float& alpha) {
;   constexpr float SCALE = (DQK == 96) ? 0.10206207261596577f : 0.125f;
;   constexpr float C = SCALE * 1.4426950408889634f;
;   float pmax = p0[0];
; #pragma unroll
;   for (int r = 1; r < 16; ++r) pmax = fmaxf(pmax, p0[r]);
; #pragma unroll
;   for (int r = 0; r < 16; ++r) pmax = fmaxf(pmax, p1[r]);
;   { auto rr = __builtin_amdgcn_permlane32_swap(__float_as_uint(pmax), __float_as_uint(pmax), false, false);
;     pmax = fmaxf(__uint_as_float(rr[0]), __uint_as_float(rr[1])); }
;   if (__builtin_expect(__all(pmax - m_reg <= THR / SCALE), 1)) { mn = m_reg; alpha = 1.f; }
;   else { mn = fmaxf(m_reg, pmax); alpha = __builtin_amdgcn_exp2f((m_reg - mn) * C); m_reg = mn; }
;   float mnC = -mn * C;
; #pragma unroll
;   for (int r = 0; r < 16; ++r) p0[r] = fmaf(p0[r], C, mnC);
; #pragma unroll
;   for (int r = 0; r < 16; ++r) p1[r] = fmaf(p1[r], C, mnC);
; #pragma unroll
;   for (int r = 0; r < 16; ++r) p0[r] = __builtin_amdgcn_exp2f(p0[r]);
; }
; template <int DQK, int MODE, int ldq, int ldk, int ldv> ...
;     ...
;   SBAR(); qkt<DQK>(pB0, pB1, K_lds + SHM_K, qr, r32, hi);
;   finishSM(pA0, pA1, alA, l_reg, pa0, pa1, pa2, pa3); SBAR();
;   pv_d0(o, vb0, pa0, pa1, pa2, pa3); BIAS(pB0, pB1, NT - 1); partialSM<DQK>(pB0, pB1, m_reg, mnB, alB);
.LBB0_312:
	v_sub_f32_e32 v116, 0, v210
	s_waitcnt vmcnt(0)
	ds_write_b128 v145, v[92:95] offset:16384
	ds_read_b128 v[32:35], v148 offset:49152
	ds_read_b128 v[36:39], v148 offset:57344
	s_waitcnt lgkmcnt(1)
	v_mfma_f32_32x32x16_bf16 v[48:63], v[32:35], v[84:87], 0
	s_waitcnt lgkmcnt(0)
	v_mfma_f32_32x32x16_bf16 v[32:47], v[36:39], v[84:87], 0
	ds_read_b128 v[84:87], v152 offset:49152
	ds_read_b128 v[88:91], v152 offset:57344
	s_waitcnt lgkmcnt(1)
	v_mfma_f32_32x32x16_bf16 v[48:63], v[84:87], v[80:83], v[48:63]
	s_waitcnt lgkmcnt(0)
	v_mfma_f32_32x32x16_bf16 v[32:47], v[88:91], v[80:83], v[32:47]
	ds_read_b128 v[80:83], v151 offset:49152
	ds_read_b128 v[84:87], v151 offset:57344
	v_mov_b32_e32 v88, v100
	v_mov_b32_e32 v89, v101
	s_waitcnt lgkmcnt(1)
	v_mfma_f32_32x32x16_bf16 v[48:63], v[80:83], v[76:79], v[48:63]
	s_waitcnt lgkmcnt(0)
	v_mfma_f32_32x32x16_bf16 v[32:47], v[84:87], v[76:79], v[32:47]
	ds_read_b128 v[76:79], v149 offset:49152
	ds_read_b128 v[80:83], v149 offset:57344
	v_mov_b32_e32 v84, v110
	v_mov_b32_e32 v85, v111
	v_mov_b32_e32 v86, v106
	v_mov_b32_e32 v87, v107
	s_waitcnt lgkmcnt(1)
	v_mfma_f32_32x32x16_bf16 v[48:63], v[76:79], v[72:75], v[48:63]
	s_waitcnt lgkmcnt(0)
	v_mfma_f32_32x32x16_bf16 v[32:47], v[80:83], v[72:75], v[32:47]
	ds_read_b128 v[72:75], v150 offset:49152
	ds_read_b128 v[76:79], v150 offset:57344
	v_mov_b32_e32 v80, v104
	v_mov_b32_e32 v81, v105
	v_mov_b32_e32 v82, v102
	v_mov_b32_e32 v83, v103
	s_waitcnt lgkmcnt(1)
	v_mfma_f32_32x32x16_bf16 v[48:63], v[72:75], v[68:71], v[48:63]
	s_waitcnt lgkmcnt(0)
	v_mfma_f32_32x32x16_bf16 v[32:47], v[76:79], v[68:71], v[32:47]
	ds_read_b128 v[68:71], v153 offset:49152
	ds_read_b128 v[72:75], v153 offset:57344
	v_mov_b32_e32 v76, v112
	v_mov_b32_e32 v77, v113
	v_mov_b32_e32 v78, v108
	v_mov_b32_e32 v79, v109
	s_waitcnt lgkmcnt(1)
	v_mfma_f32_32x32x16_bf16 v[48:63], v[68:71], v[64:67], v[48:63]
	s_waitcnt lgkmcnt(0)
	v_mfma_f32_32x32x16_bf16 v[32:47], v[72:75], v[64:67], v[32:47]
	v_add_f32_e32 v64, 0, v126
	v_add_f32_e32 v64, v160, v64
	v_add_f32_e32 v64, v127, v64
	v_add_f32_e32 v64, v161, v64
	v_add_f32_e32 v64, v158, v64
	v_add_f32_e32 v64, v162, v64
	v_add_f32_e32 v64, v159, v64
	v_add_f32_e32 v64, v163, v64
	v_add_f32_e32 v64, v118, v64
	v_add_f32_e32 v64, v121, v64
	v_add_f32_e32 v64, v119, v64
	v_add_f32_e32 v64, v122, v64
	v_mov_b32_e32 v74, v114
	v_add_f32_e32 v64, v120, v64
	v_mov_b32_e32 v75, v115
	v_add_f32_e32 v64, v123, v64
	v_add_f32_e32 v64, v124, v64
	v_add_f32_e32 v64, v125, v64
	v_add_f32_e32 v64, v74, v64
	v_add_f32_e32 v64, v75, v64
	v_add_f32_e32 v64, v76, v64
	v_add_f32_e32 v64, v77, v64
	v_add_f32_e32 v64, v78, v64
	v_add_f32_e32 v64, v79, v64
	v_add_f32_e32 v64, v80, v64
	v_add_f32_e32 v64, v81, v64
	v_add_f32_e32 v64, v82, v64
	v_add_f32_e32 v64, v83, v64
	v_add_f32_e32 v64, v84, v64
	v_add_f32_e32 v64, v85, v64
	v_add_f32_e32 v64, v86, v64
	v_add_f32_e32 v64, v87, v64
	v_add_f32_e32 v64, v88, v64
	v_add_f32_e32 v64, v89, v64
	v_mov_b32_e32 v65, v64
	v_cvt_pk_bf16_f32 v66, v126, v160
	v_cvt_pk_bf16_f32 v67, v127, v161
	v_cvt_pk_bf16_f32 v68, v158, v162
	v_cvt_pk_bf16_f32 v69, v159, v163
	s_nop 1
	v_permlane32_swap_b32_e32 v64, v65
	v_cvt_pk_bf16_f32 v70, v118, v121
	v_cvt_pk_bf16_f32 v71, v119, v122
	v_cvt_pk_bf16_f32 v72, v120, v123
	v_cvt_pk_bf16_f32 v73, v124, v125
	v_cvt_pk_bf16_f32 v74, v74, v75
	v_cvt_pk_bf16_f32 v75, v76, v77
	v_cvt_pk_bf16_f32 v76, v78, v79
	v_cvt_pk_bf16_f32 v77, v80, v81
	v_cvt_pk_bf16_f32 v78, v82, v83
	v_cvt_pk_bf16_f32 v79, v84, v85
	v_cvt_pk_bf16_f32 v80, v86, v87
	v_cvt_pk_bf16_f32 v81, v88, v89
	s_nop 0
	ds_read_b64_tr_b16 v[82:83], v144 offset:0
	ds_read_b64_tr_b16 v[84:85], v144 offset:0x800
	ds_read_b64_tr_b16 v[86:87], v144 offset:0x1000
	ds_read_b64_tr_b16 v[88:89], v144 offset:0x1800
	ds_read_b64_tr_b16 v[90:91], v144 offset:0x2000
	ds_read_b64_tr_b16 v[92:93], v144 offset:0x2800
	ds_read_b64_tr_b16 v[94:95], v144 offset:0x3000
	ds_read_b64_tr_b16 v[96:97], v144 offset:0x3800
	s_waitcnt lgkmcnt(0)
	s_nop 0
	v_mfma_f32_32x32x16_bf16 v[0:15], v[66:69], v[82:85], v[0:15]
	ds_read_b64_tr_b16 v[82:83], v144 offset:0x200
	ds_read_b64_tr_b16 v[84:85], v144 offset:0xa00
	v_mfma_f32_32x32x16_bf16 v[0:15], v[70:73], v[86:89], v[0:15]
	ds_read_b64_tr_b16 v[86:87], v144 offset:0x1200
	ds_read_b64_tr_b16 v[88:89], v144 offset:0x1a00
	v_mfma_f32_32x32x16_bf16 v[0:15], v[74:77], v[90:93], v[0:15]
	ds_read_b64_tr_b16 v[90:91], v144 offset:0x2200
	ds_read_b64_tr_b16 v[92:93], v144 offset:0x2a00
	v_mfma_f32_32x32x16_bf16 v[0:15], v[78:81], v[94:97], v[0:15]
	ds_read_b64_tr_b16 v[94:95], v144 offset:0x3200
	ds_read_b64_tr_b16 v[96:97], v144 offset:0x3a00
	s_waitcnt lgkmcnt(0)
	v_mfma_f32_32x32x16_bf16 v[16:31], v[66:69], v[82:85], v[16:31]
	v_max_f32_e32 v66, v49, v49
	v_max_f32_e32 v67, v48, v48
	v_max_f32_e32 v66, v67, v66
	v_max3_f32 v66, v66, v50, v51
	v_max3_f32 v66, v66, v52, v53
	v_max3_f32 v66, v66, v54, v55
	v_max3_f32 v66, v66, v56, v57
	v_max3_f32 v66, v66, v58, v59
	v_max3_f32 v66, v66, v60, v61
	v_mfma_f32_32x32x16_bf16 v[16:31], v[70:73], v[86:89], v[16:31]
	v_max3_f32 v66, v66, v62, v63
	v_max3_f32 v66, v66, v32, v33
	v_max3_f32 v66, v66, v34, v35
	v_max3_f32 v66, v66, v36, v37
	v_max3_f32 v66, v66, v38, v39
	v_max3_f32 v66, v66, v40, v41
	v_max3_f32 v66, v66, v42, v43
	v_max3_f32 v66, v66, v44, v45
	v_mfma_f32_32x32x16_bf16 v[16:31], v[74:77], v[90:93], v[16:31]
	v_max3_f32 v66, v66, v46, v47
	v_mov_b32_e32 v67, v66
	s_nop 1
	v_permlane32_swap_b32_e32 v66, v67
	v_max_f32_e32 v67, v67, v67
	v_max_f32_e32 v66, v66, v66
	v_max_f32_e32 v66, v66, v67
	v_sub_f32_e32 v67, v66, v116
	v_cmp_ge_f32_e32 vcc, s80, v67
	v_max_f32_e32 v67, v116, v116
	v_max_f32_e32 v67, v67, v66
	v_mfma_f32_32x32x16_bf16 v[16:31], v[78:81], v[94:97], v[16:31]
	v_sub_f32_e32 v66, v116, v67
	v_mul_f32_e32 v66, 0x3f800000, v66
	v_exp_f32_e32 v66, v66
	s_cmp_eq_u64 vcc, exec
	s_cselect_b64 s[0:1], -1, 0
	v_cndmask_b32_e64 v66, v66, 1.0, s[0:1]
	v_cmp_gt_f32_e32 vcc, 1.0, v66
	s_barrier
; #define SBAR() __builtin_amdgcn_sched_barrier(0)
; #define RESC(a) do { if (__any((a) < 1.f)) { if (hi == 0) al_l[r32] = (a); asm volatile("s_waitcnt lgkmcnt(0)" ::: "memory"); \
;     _Pragma("unroll") for (int d = 0; d < 2; ++d) _Pragma("unroll") for (int r = 0; r < 16; ++r) o[d][r] *= al_l[crow(r, hi)]; } } while (0)
; template <int DQK> __device__ __forceinline__ void partialSM(f32x16& p0, f32x16& p1, float& m_reg, float& mn, float& alpha) {
;   constexpr float SCALE = (DQK == 96) ? 0.10206207261596577f : 0.125f;
;   constexpr float C = SCALE * 1.4426950408889634f;
;   float pmax = p0[0];
; #pragma unroll
;   for (int r = 1; r < 16; ++r) pmax = fmaxf(pmax, p0[r]);
; #pragma unroll
;   for (int r = 0; r < 16; ++r) pmax = fmaxf(pmax, p1[r]);
;   { auto rr = __builtin_amdgcn_permlane32_swap(__float_as_uint(pmax), __float_as_uint(pmax), false, false);
;     pmax = fmaxf(__uint_as_float(rr[0]), __uint_as_float(rr[1])); }
;   if (__builtin_expect(__all(pmax - m_reg <= THR / SCALE), 1)) { mn = m_reg; alpha = 1.f; }
;   else { mn = fmaxf(m_reg, pmax); alpha = __builtin_amdgcn_exp2f((m_reg - mn) * C); m_reg = mn; }
;   float mnC = -mn * C;
; #pragma unroll
;   for (int r = 0; r < 16; ++r) p0[r] = fmaf(p0[r], C, mnC);
; #pragma unroll
;   for (int r = 0; r < 16; ++r) p1[r] = fmaf(p1[r], C, mnC);
; #pragma unroll
;   for (int r = 0; r < 16; ++r) p0[r] = __builtin_amdgcn_exp2f(p0[r]);
; }
; __device__ __forceinline__ void finishSM(f32x16& p0, f32x16& p1, float alpha, float& l_reg, bf16x8& pa0, bf16x8& pa1, bf16x8& pa2, bf16x8& pa3) {
; #pragma unroll
;   for (int r = 0; r < 16; ++r) p1[r] = __builtin_amdgcn_exp2f(p1[r]);
;   float ps = 0;
; #pragma unroll
;   for (int r = 0; r < 16; ++r) ps += p0[r];
; #pragma unroll
;   for (int r = 0; r < 16; ++r) ps += p1[r];
;   { auto rr = __builtin_amdgcn_permlane32_swap(__float_as_uint(ps), __float_as_uint(ps), false, false);
;     ps = __uint_as_float(rr[0]) + __uint_as_float(rr[1]); }
;   l_reg = l_reg * alpha + ps;
;     ...
;   PK4(p0, 0, pa0); PK4(p0, 8, pa1); PK4(p1, 0, pa2); PK4(p1, 8, pa3);
; template <int DQK, int MODE, int ldq, int ldk, int ldv> ...
;     ...
;   __syncthreads(); RESC(alB);
;   finishSM(pB0, pB1, alB, l_reg, pa0, pa1, pa2, pa3); SBAR();
;   pv_d0(o, vb0 + (int)SHM_V, pa0, pa1, pa2, pa3);
;   if (hi == 0) li_l[r32] = l_reg; asm volatile("s_waitcnt lgkmcnt(0)" ::: "memory");
	s_cbranch_vccz .LBB0_316
	s_and_saveexec_b64 s[10:11], s[4:5]
	ds_write_b32 v141, v66 offset:128
	s_or_b64 exec, exec, s[10:11]
	s_waitcnt lgkmcnt(0)
	ds_read_b128 v[68:71], v129 offset:224
	ds_read_b128 v[72:75], v129 offset:192
	ds_read_b128 v[76:79], v129 offset:160
	ds_read_b128 v[80:83], v129 offset:128
	s_waitcnt lgkmcnt(3)
	v_pk_mul_f32 v[14:15], v[14:15], v[70:71]
	s_waitcnt lgkmcnt(2)
	v_pk_mul_f32 v[10:11], v[10:11], v[74:75]
	s_waitcnt lgkmcnt(1)
	v_pk_mul_f32 v[6:7], v[6:7], v[78:79]
	s_waitcnt lgkmcnt(0)
	v_pk_mul_f32 v[2:3], v[2:3], v[82:83]
	v_pk_mul_f32 v[12:13], v[12:13], v[68:69]
	v_pk_mul_f32 v[8:9], v[8:9], v[72:73]
	v_pk_mul_f32 v[4:5], v[4:5], v[76:77]
	v_pk_mul_f32 v[0:1], v[0:1], v[80:81]
	v_pk_mul_f32 v[30:31], v[30:31], v[70:71]
	v_pk_mul_f32 v[26:27], v[26:27], v[74:75]
	v_pk_mul_f32 v[22:23], v[22:23], v[78:79]
	v_pk_mul_f32 v[18:19], v[18:19], v[82:83]
	v_pk_mul_f32 v[28:29], v[28:29], v[68:69]
	v_pk_mul_f32 v[24:25], v[24:25], v[72:73]
	v_pk_mul_f32 v[20:21], v[20:21], v[76:77]
	v_pk_mul_f32 v[16:17], v[16:17], v[80:81]
.LBB0_316:
	v_cndmask_b32_e64 v67, v67, v116, s[0:1]
	v_mul_f32_e32 v67, 0xbf800000, v67
	v_fmamk_f32 v48, v48, 0x3f800000, v67
	v_fmamk_f32 v49, v49, 0x3f800000, v67
	v_fmamk_f32 v68, v50, 0x3f800000, v67
	v_exp_f32_e32 v50, v48
	v_fmamk_f32 v69, v52, 0x3f800000, v67
	v_exp_f32_e32 v52, v49
	v_fmamk_f32 v51, v51, 0x3f800000, v67
	v_exp_f32_e32 v48, v68
	v_fmamk_f32 v32, v32, 0x3f800000, v67
	v_exp_f32_e32 v51, v51
	v_fmamk_f32 v70, v53, 0x3f800000, v67
	v_fmamk_f32 v79, v62, 0x3f800000, v67
	v_fmamk_f32 v62, v43, 0x3f800000, v67
	v_exp_f32_e32 v43, v69
	v_exp_f32_e32 v68, v32
	v_add_f32_e32 v32, 0, v50
	v_fmamk_f32 v71, v54, 0x3f800000, v67
	v_exp_f32_e32 v49, v70
	v_add_f32_e32 v32, v52, v32
	v_fmamk_f32 v72, v55, 0x3f800000, v67
	v_fmamk_f32 v78, v61, 0x3f800000, v67
	v_fmamk_f32 v61, v42, 0x3f800000, v67
	v_exp_f32_e32 v42, v71
	v_add_f32_e32 v32, v48, v32
	v_fmamk_f32 v73, v56, 0x3f800000, v67
	v_fmamk_f32 v80, v63, 0x3f800000, v67
	v_fmamk_f32 v63, v44, 0x3f800000, v67
	v_exp_f32_e32 v44, v72
	v_add_f32_e32 v32, v51, v32
	v_fmamk_f32 v74, v57, 0x3f800000, v67
	v_fmamk_f32 v75, v58, 0x3f800000, v67
	v_fmamk_f32 v58, v39, 0x3f800000, v67
	v_exp_f32_e32 v39, v73
	v_add_f32_e32 v32, v43, v32
	v_fmamk_f32 v77, v60, 0x3f800000, v67
	v_fmamk_f32 v60, v41, 0x3f800000, v67
	v_exp_f32_e32 v41, v74
	v_add_f32_e32 v32, v49, v32
	v_fmamk_f32 v76, v59, 0x3f800000, v67
	v_fmamk_f32 v56, v37, 0x3f800000, v67
	v_exp_f32_e32 v37, v75
	v_add_f32_e32 v32, v42, v32
	v_fmamk_f32 v59, v40, 0x3f800000, v67
	v_exp_f32_e32 v40, v76
	v_add_f32_e32 v32, v44, v32
	v_fmamk_f32 v54, v35, 0x3f800000, v67
	v_exp_f32_e32 v35, v77
	v_add_f32_e32 v32, v39, v32
	v_fmamk_f32 v57, v38, 0x3f800000, v67
	v_exp_f32_e32 v38, v78
	v_add_f32_e32 v32, v41, v32
	v_fmamk_f32 v53, v34, 0x3f800000, v67
	v_exp_f32_e32 v34, v79
	v_add_f32_e32 v32, v37, v32
	v_fmamk_f32 v55, v36, 0x3f800000, v67
	v_exp_f32_e32 v36, v80
	v_add_f32_e32 v32, v40, v32
	v_fmamk_f32 v33, v33, 0x3f800000, v67
	v_add_f32_e32 v32, v35, v32
	v_exp_f32_e32 v69, v33
	v_add_f32_e32 v32, v38, v32
	v_exp_f32_e32 v53, v53
	v_add_f32_e32 v32, v34, v32
	v_exp_f32_e32 v54, v54
	v_add_f32_e32 v32, v36, v32
	v_exp_f32_e32 v55, v55
	v_add_f32_e32 v32, v68, v32
	v_exp_f32_e32 v56, v56
	v_add_f32_e32 v32, v69, v32
	v_exp_f32_e32 v57, v57
	v_add_f32_e32 v32, v53, v32
	v_exp_f32_e32 v58, v58
	v_add_f32_e32 v32, v54, v32
	v_exp_f32_e32 v59, v59
	v_add_f32_e32 v32, v55, v32
	v_exp_f32_e32 v60, v60
	v_add_f32_e32 v32, v56, v32
	v_exp_f32_e32 v61, v61
	v_add_f32_e32 v32, v57, v32
	v_exp_f32_e32 v62, v62
	v_add_f32_e32 v32, v58, v32
	v_fmamk_f32 v45, v45, 0x3f800000, v67
	v_exp_f32_e32 v63, v63
	v_add_f32_e32 v32, v59, v32
	v_fmamk_f32 v46, v46, 0x3f800000, v67
	v_exp_f32_e32 v70, v45
	v_add_f32_e32 v32, v60, v32
	v_fmac_f32_e32 v67, 0x3f800000, v47
	v_exp_f32_e32 v71, v46
	v_add_f32_e32 v32, v61, v32
	v_exp_f32_e32 v67, v67
	v_add_f32_e32 v32, v62, v32
	v_add_f32_e32 v32, v63, v32
	v_add_f32_e32 v32, v70, v32
	v_add_f32_e32 v32, v71, v32
	v_add_f32_e32 v32, v67, v32
	v_mov_b32_e32 v33, v32
	s_nop 1
	v_permlane32_swap_b32_e32 v32, v33
	v_cvt_pk_bf16_f32 v46, v50, v52
	v_cvt_pk_bf16_f32 v47, v48, v51
	v_cvt_pk_bf16_f32 v48, v43, v49
	v_cvt_pk_bf16_f32 v49, v42, v44
	v_cvt_pk_bf16_f32 v42, v39, v41
	v_cvt_pk_bf16_f32 v43, v37, v40
	v_cvt_pk_bf16_f32 v44, v35, v38
	v_cvt_pk_bf16_f32 v45, v34, v36
	v_cvt_pk_bf16_f32 v34, v68, v69
	v_cvt_pk_bf16_f32 v35, v53, v54
	v_cvt_pk_bf16_f32 v36, v55, v56
	v_cvt_pk_bf16_f32 v37, v57, v58
	v_cvt_pk_bf16_f32 v38, v59, v60
	v_cvt_pk_bf16_f32 v39, v61, v62
	v_cvt_pk_bf16_f32 v40, v63, v70
	v_cvt_pk_bf16_f32 v41, v71, v67
	s_nop 0
	ds_read_b64_tr_b16 v[50:51], v143 offset:0
	ds_read_b64_tr_b16 v[52:53], v143 offset:0x800
	ds_read_b64_tr_b16 v[54:55], v143 offset:0x1000
	ds_read_b64_tr_b16 v[56:57], v143 offset:0x1800
	ds_read_b64_tr_b16 v[58:59], v143 offset:0x2000
	ds_read_b64_tr_b16 v[60:61], v143 offset:0x2800
	ds_read_b64_tr_b16 v[68:69], v143 offset:0x3000
	ds_read_b64_tr_b16 v[70:71], v143 offset:0x3800
	s_waitcnt lgkmcnt(0)
	s_nop 0
	v_mfma_f32_32x32x16_bf16 v[0:15], v[46:49], v[50:53], v[0:15]
	ds_read_b64_tr_b16 v[50:51], v143 offset:0x200
	ds_read_b64_tr_b16 v[52:53], v143 offset:0xa00
	v_mfma_f32_32x32x16_bf16 v[0:15], v[42:45], v[54:57], v[0:15]
	ds_read_b64_tr_b16 v[54:55], v143 offset:0x1200
	ds_read_b64_tr_b16 v[56:57], v143 offset:0x1a00
	v_mfma_f32_32x32x16_bf16 v[0:15], v[34:37], v[58:61], v[0:15]
	ds_read_b64_tr_b16 v[58:59], v143 offset:0x2200
	ds_read_b64_tr_b16 v[60:61], v143 offset:0x2a00
	v_mfma_f32_32x32x16_bf16 v[0:15], v[38:41], v[68:71], v[0:15]
	ds_read_b64_tr_b16 v[68:69], v143 offset:0x3200
	ds_read_b64_tr_b16 v[70:71], v143 offset:0x3a00
	s_waitcnt lgkmcnt(0)
	v_mfma_f32_32x32x16_bf16 v[16:31], v[46:49], v[50:53], v[16:31]
	v_mfma_f32_32x32x16_bf16 v[16:31], v[42:45], v[54:57], v[16:31]
	v_mfma_f32_32x32x16_bf16 v[16:31], v[34:37], v[58:61], v[16:31]
	v_mfma_f32_32x32x16_bf16 v[16:31], v[38:41], v[68:71], v[16:31]
	s_and_saveexec_b64 s[0:1], s[4:5]
	s_cbranch_execz .LBB0_298
	v_add_f32_e32 v34, v64, v65
	v_fmac_f32_e32 v34, v142, v117
	v_add_f32_e32 v32, v32, v33
	v_fmac_f32_e32 v32, v34, v66
	ds_write_b32 v141, v32
	s_branch .LBB0_298
